# NX: next-tile K-tile-0 loads issued before epilogue stores in in-proj and MLP-up GEMMs; scan producer b16 scatter replaced by row-major b64 writes + transpose reads
# speedup vs baseline: 1.1035x; 1.0036x over previous
.LBB0_124:
	s_andn2_b64 vcc, exec, s[2:3]
	s_cbranch_vccnz .LBB0_177
	s_mov_b32 s98, 0
	v_mov_b32_e32 v2, v1
	s_load_dword s2, s[72:73], 0x10
	s_load_dwordx2 s[22:23], s[0:1], 0xf8
	v_ashrrev_i32_e32 v3, 1, v2
	v_and_b32_e32 v4, 15, v2
	v_and_or_b32 v35, v3, s87, v4
	v_lshrrev_b32_e32 v3, 1, v2
	s_waitcnt lgkmcnt(0)
	s_add_u32 s24, s22, 0x1340000
	s_addc_u32 s40, s23, 0
	s_lshr_b32 s2, s2, 16
	s_cmp_lg_u32 s2, 0
	s_cselect_b64 s[2:3], -1, 0
	s_cmp_lg_u64 s[2:3], 0
	s_addc_u32 s2, s74, 0
	s_lshr_b32 s41, s2, 3
	v_and_b32_e32 v3, 24, v3
	s_movk_i32 s2, 0xc0
	s_mov_b32 s33, 0
	v_and_or_b32 v226, v2, s2, v3
	s_branch .LBB0_127

.LBB0_132:
	s_cmp_eq_u32 s98, 1
	s_cbranch_scc1 .Lnxk9_pre
	v_mov_b32_e32 v15, v1
	s_ashr_i32 s3, s2, 31
	v_ashrrev_i32_e32 v3, 3, v15
	v_and_b32_e32 v4, 7, v15
	v_lshlrev_b32_e32 v2, 1, v3
	s_lshl_b64 s[30:31], s[2:3], 19
	v_lshlrev_b32_e32 v227, 3, v4
	v_and_b32_e32 v14, 24, v2
	v_lshrrev_b32_e32 v2, 2, v3
	v_lshlrev_b32_e32 v228, 10, v3
	s_add_u32 s30, s16, s30
	v_and_b32_e32 v16, 4, v2
	v_and_b32_e32 v17, 35, v3
	v_or_b32_e32 v2, v228, v227
	v_bitop3_b32 v3, v3, v15, 7 bitop3:0x78
	s_addc_u32 s31, s17, s31
	v_or3_b32 v5, v17, v14, v16
	v_lshl_add_u32 v9, v4, 8, v3
	v_mov_b32_e32 v3, v34
	v_add_u32_e32 v6, 0x10000, v2
	v_mov_b32_e32 v7, v34
	v_lshl_or_b32 v8, v5, 10, v227
	s_mov_b32 s3, 16
	v_lshl_add_u64 v[4:5], v[2:3], 1, s[30:31]
	v_lshl_add_u64 v[6:7], v[6:7], 1, s[30:31]
	global_load_dwordx4 v[116:119], v[4:5], off
	global_load_dwordx4 v[120:123], v[6:7], off
	v_add_u32_e32 v6, 0x20000, v2
	v_mov_b32_e32 v7, v34
	v_lshl_add_u64 v[6:7], v[6:7], 1, s[30:31]
	s_ashr_i32 s23, s22, 31
	global_load_dwordx4 v[128:131], v[6:7], off
	v_add_u32_e32 v6, 0x30000, v2
	v_mov_b32_e32 v7, v34
	s_lshl_b64 s[38:39], s[22:23], 19
	v_lshl_add_u64 v[6:7], v[6:7], 1, s[30:31]
	s_add_u32 s38, s24, s38
	global_load_dwordx4 v[136:139], v[6:7], off
	v_lshlrev_b32_e32 v6, 1, v8
	s_addc_u32 s39, s40, s39
	v_or_b32_e32 v8, 0x20000, v6
	v_or_b32_e32 v10, 0x40000, v6
	v_or_b32_e32 v12, 0x60000, v6
	global_load_dwordx4 v[140:143], v6, s[38:39]
	global_load_dwordx4 v[144:147], v8, s[38:39]
	global_load_dwordx4 v[152:155], v10, s[38:39]
	global_load_dwordx4 v[160:163], v12, s[38:39]
	v_lshl_add_u32 v229, v9, 4, 0
	v_add_u32_e32 v230, 0x10000, v229
	s_cmp_lt_i32 s3, 2
	s_waitcnt vmcnt(7)
	ds_write_b128 v229, v[116:119]
	s_waitcnt vmcnt(6)
	ds_write_b128 v229, v[120:123] offset:1024
	s_waitcnt vmcnt(5)
	ds_write_b128 v229, v[128:131] offset:2048
	s_waitcnt vmcnt(4)
	ds_write_b128 v229, v[136:139] offset:3072
	s_waitcnt vmcnt(3)
	ds_write_b128 v230, v[140:143]
	s_waitcnt vmcnt(2)
	ds_write_b128 v230, v[144:147] offset:1024
	s_waitcnt vmcnt(1)
	ds_write_b128 v230, v[152:155] offset:2048
	s_waitcnt vmcnt(0)
	ds_write_b128 v230, v[160:163] offset:3072
	s_cbranch_scc1 .LBB0_134
	v_add_u32_e32 v20, 0x20040, v2
	v_mov_b32_e32 v21, v34
	v_mov_b32_e32 v7, v34
	v_mov_b32_e32 v9, v34
	v_mov_b32_e32 v11, v34
	v_mov_b32_e32 v13, v34
	v_add_u32_e32 v18, 0x10040, v2
	v_mov_b32_e32 v19, v34
	v_lshl_add_u64 v[20:21], v[20:21], 1, s[30:31]
	v_add_u32_e32 v2, 0x30040, v2
	v_mov_b32_e32 v3, v34
	v_lshl_add_u64 v[6:7], s[38:39], 0, v[6:7]
	v_lshl_add_u64 v[8:9], s[38:39], 0, v[8:9]
	v_lshl_add_u64 v[10:11], s[38:39], 0, v[10:11]
	v_lshl_add_u64 v[12:13], s[38:39], 0, v[12:13]
	v_lshl_add_u64 v[18:19], v[18:19], 1, s[30:31]
	v_lshl_add_u64 v[2:3], v[2:3], 1, s[30:31]
	global_load_dwordx4 v[116:119], v[4:5], off offset:128
	global_load_dwordx4 v[120:123], v[18:19], off
	global_load_dwordx4 v[128:131], v[20:21], off
	global_load_dwordx4 v[136:139], v[2:3], off
	global_load_dwordx4 v[140:143], v[6:7], off offset:128
	global_load_dwordx4 v[144:147], v[8:9], off offset:128
	global_load_dwordx4 v[152:155], v[10:11], off offset:128
	global_load_dwordx4 v[160:163], v[12:13], off offset:128

.Lnxk9_pre:
	s_mov_b32 s98, 0
	v_mov_b32_e32 v15, v1
	s_ashr_i32 s3, s2, 31
	v_ashrrev_i32_e32 v3, 3, v15
	v_and_b32_e32 v4, 7, v15
	v_lshlrev_b32_e32 v2, 1, v3
	s_lshl_b64 s[30:31], s[2:3], 19
	v_lshlrev_b32_e32 v227, 3, v4
	v_and_b32_e32 v14, 24, v2
	v_lshrrev_b32_e32 v2, 2, v3
	v_lshlrev_b32_e32 v228, 10, v3
	s_add_u32 s30, s16, s30
	v_and_b32_e32 v16, 4, v2
	v_and_b32_e32 v17, 35, v3
	v_or_b32_e32 v2, v228, v227
	v_bitop3_b32 v3, v3, v15, 7 bitop3:0x78
	s_addc_u32 s31, s17, s31
	v_or3_b32 v5, v17, v14, v16
	v_lshl_add_u32 v9, v4, 8, v3
	v_mov_b32_e32 v3, v34
	v_add_u32_e32 v6, 0x10000, v2
	v_mov_b32_e32 v7, v34
	v_lshl_or_b32 v8, v5, 10, v227
	s_mov_b32 s3, 16
	v_lshl_add_u64 v[4:5], v[2:3], 1, s[30:31]
	v_lshl_add_u64 v[6:7], v[6:7], 1, s[30:31]
	v_add_u32_e32 v6, 0x20000, v2
	v_mov_b32_e32 v7, v34
	v_lshl_add_u64 v[6:7], v[6:7], 1, s[30:31]
	s_ashr_i32 s23, s22, 31
	v_add_u32_e32 v6, 0x30000, v2
	v_mov_b32_e32 v7, v34
	s_lshl_b64 s[38:39], s[22:23], 19
	v_lshl_add_u64 v[6:7], v[6:7], 1, s[30:31]
	s_add_u32 s38, s24, s38
	v_lshlrev_b32_e32 v6, 1, v8
	s_addc_u32 s39, s40, s39
	v_or_b32_e32 v8, 0x20000, v6
	v_or_b32_e32 v10, 0x40000, v6
	v_or_b32_e32 v12, 0x60000, v6
	v_lshl_add_u32 v229, v9, 4, 0
	v_add_u32_e32 v230, 0x10000, v229
	s_cmp_lt_i32 s3, 2
	s_waitcnt vmcnt(23)
	ds_write_b128 v229, v[164:167]
	s_waitcnt vmcnt(22)
	ds_write_b128 v229, v[168:171] offset:1024
	s_waitcnt vmcnt(21)
	ds_write_b128 v229, v[172:175] offset:2048
	s_waitcnt vmcnt(20)
	ds_write_b128 v229, v[192:195] offset:3072
	s_waitcnt vmcnt(19)
	ds_write_b128 v230, v[176:179]
	s_waitcnt vmcnt(18)
	ds_write_b128 v230, v[180:183] offset:1024
	s_waitcnt vmcnt(17)
	ds_write_b128 v230, v[184:187] offset:2048
	s_waitcnt vmcnt(16)
	ds_write_b128 v230, v[188:191] offset:3072
	s_cbranch_scc1 .LBB0_134
	v_add_u32_e32 v20, 0x20040, v2
	v_mov_b32_e32 v21, v34
	v_mov_b32_e32 v7, v34
	v_mov_b32_e32 v9, v34
	v_mov_b32_e32 v11, v34
	v_mov_b32_e32 v13, v34
	v_add_u32_e32 v18, 0x10040, v2
	v_mov_b32_e32 v19, v34
	v_lshl_add_u64 v[20:21], v[20:21], 1, s[30:31]
	v_add_u32_e32 v2, 0x30040, v2
	v_mov_b32_e32 v3, v34
	v_lshl_add_u64 v[6:7], s[38:39], 0, v[6:7]
	v_lshl_add_u64 v[8:9], s[38:39], 0, v[8:9]
	v_lshl_add_u64 v[10:11], s[38:39], 0, v[10:11]
	v_lshl_add_u64 v[12:13], s[38:39], 0, v[12:13]
	v_lshl_add_u64 v[18:19], v[18:19], 1, s[30:31]
	v_lshl_add_u64 v[2:3], v[2:3], 1, s[30:31]
	global_load_dwordx4 v[116:119], v[4:5], off offset:128
	global_load_dwordx4 v[120:123], v[18:19], off
	global_load_dwordx4 v[128:131], v[20:21], off
	global_load_dwordx4 v[136:139], v[2:3], off
	global_load_dwordx4 v[140:143], v[6:7], off offset:128
	global_load_dwordx4 v[144:147], v[8:9], off offset:128
	global_load_dwordx4 v[152:155], v[10:11], off offset:128
	global_load_dwordx4 v[160:163], v[12:13], off offset:128
	s_branch .LBB0_134

.LBB0_142:
	s_waitcnt vmcnt(5)
	v_lshl_add_u32 v118, s2, 8, v35
	v_ashrrev_i32_e32 v119, 31, v118
	v_lshl_or_b32 v116, s22, 8, v226
	s_waitcnt vmcnt(1)
	s_add_i32 s3, s33, 1
	s_mul_i32 s23, s3, s41
	s_mul_hi_u32 s3, s3, s41
	s_add_u32 s38, s23, s37
	s_addc_u32 s39, s3, 0
	s_lshr_b64 s[30:31], s[38:39], 2
	s_and_b32 s3, s30, -8
	s_or_b32 s23, s3, s35
	s_mov_b32 s98, 0
	s_cmp_gt_i32 s23, 63
	s_cbranch_scc1 .Lnxk9_skip
	s_lshr_b32 s3, s23, 1
	s_lshl_b32 s3, s3, 2
	s_and_b32 s30, s38, 3
	s_or_b32 s3, s3, s30
	s_and_b32 s30, s23, 1
	s_lshl_b32 s30, s30, 3
	s_bfe_u32 s31, s38, 0x30002
	s_or_b32 s30, s30, s31
	s_lshl_b32 s3, s3, 19
	s_lshl_b32 s30, s30, 19
	s_add_u32 s98, s16, s3
	s_addc_u32 s99, s17, 0
	s_add_u32 s100, s24, s30
	s_addc_u32 s101, s40, 0
	s_sub_u32 s98, s98, 1920
	s_subb_u32 s99, s99, 0
	s_sub_u32 s100, s100, 1920
	s_subb_u32 s101, s101, 0
	v_add_u32_e32 v246, v227, v228
	v_add_u32_e32 v247, v227, v231
	v_lshlrev_b32_e32 v246, 1, v246
	v_lshlrev_b32_e32 v247, 1, v247
	v_add_u32_e32 v248, 0x20000, v246
	v_add_u32_e32 v249, 0x40000, v246
	v_add_u32_e32 v250, 0x60000, v246
	v_add_u32_e32 v251, 0x20000, v247
	v_add_u32_e32 v252, 0x40000, v247
	v_add_u32_e32 v253, 0x60000, v247
	global_load_dwordx4 v[164:167], v246, s[98:99]
	global_load_dwordx4 v[168:171], v248, s[98:99]
	global_load_dwordx4 v[172:175], v249, s[98:99]
	global_load_dwordx4 v[192:195], v250, s[98:99]
	global_load_dwordx4 v[176:179], v247, s[100:101]
	global_load_dwordx4 v[180:183], v251, s[100:101]
	global_load_dwordx4 v[184:187], v252, s[100:101]
	global_load_dwordx4 v[188:191], v253, s[100:101]
	s_mov_b32 s98, 1
.Lnxk9_skip:
	v_lshlrev_b64 v[120:121], 13, v[118:119]
	s_movk_i32 s3, 0x1000
	v_lshl_add_u64 v[120:121], s[18:19], 0, v[120:121]
	v_cmp_gt_i32_e32 vcc, s3, v116
	v_ashrrev_i32_e32 v117, 31, v116
	s_and_saveexec_b64 s[30:31], vcc
	s_cbranch_execz .LBB0_144
	v_max_f32_e32 v119, v156, v156
	v_max_f32_e32 v128, 0, v119
	v_max_f32_e32 v119, v157, v157
	v_max_f32_e32 v129, 0, v119
	v_max_f32_e32 v119, v158, v158
	v_max_f32_e32 v130, 0, v119
	v_max_f32_e32 v119, v159, v159
	v_max_f32_e32 v131, 0, v119
	v_max_f32_e32 v119, v148, v148
	v_max_f32_e32 v136, 0, v119
	v_max_f32_e32 v119, v149, v149
	v_max_f32_e32 v137, 0, v119
	v_max_f32_e32 v119, v150, v150
	v_max_f32_e32 v138, 0, v119
	v_max_f32_e32 v119, v151, v151
	v_max_f32_e32 v139, 0, v119
	v_pk_mul_f32 v[128:129], v[128:129], v[128:129]
	v_pk_mul_f32 v[130:131], v[130:131], v[130:131]
	v_cvt_pk_f16_f32 v128, v128, v129
	v_cvt_pk_f16_f32 v129, v130, v131
	v_pk_mul_f32 v[130:131], v[136:137], v[136:137]
	v_pk_mul_f32 v[136:137], v[138:139], v[138:139]
	v_lshl_add_u64 v[122:123], v[116:117], 1, v[120:121]
	v_cvt_pk_f16_f32 v130, v130, v131
	v_cvt_pk_f16_f32 v131, v136, v137
	global_store_dwordx4 v[122:123], v[128:131], off

.LBB0_331:
	s_or_b64 exec, exec, s[58:59]
	s_lshl_b32 s33, s97, 2
	s_and_b32 s33, s33, 4
	s_lshl_b64 s[58:59], s[62:63], 2
	s_waitcnt lgkmcnt(0)
	s_add_u32 s60, s68, s58
	s_addc_u32 s61, s69, s59
	v_lshlrev_b32_e32 v160, 2, v148
	s_nop 0
	s_waitcnt vmcnt(8)
	v_cvt_f32_f16_e32 v236, v100
	v_cvt_f32_f16_sdwa v234, v100 dst_sel:DWORD dst_unused:UNUSED_PAD src0_sel:WORD_1
	v_cvt_f32_f16_e32 v232, v101
	v_cvt_f32_f16_sdwa v230, v101 dst_sel:DWORD dst_unused:UNUSED_PAD src0_sel:WORD_1
	v_cvt_f32_f16_e32 v229, v102
	v_cvt_f32_f16_sdwa v227, v102 dst_sel:DWORD dst_unused:UNUSED_PAD src0_sel:WORD_1
	v_cvt_f32_f16_e32 v211, v103
	v_cvt_f32_f16_sdwa v209, v103 dst_sel:DWORD dst_unused:UNUSED_PAD src0_sel:WORD_1
	v_cvt_f32_f16_e32 v109, v92
	v_cvt_f32_f16_sdwa v243, v92 dst_sel:DWORD dst_unused:UNUSED_PAD src0_sel:WORD_1
	v_cvt_f32_f16_e32 v242, v93
	v_cvt_f32_f16_sdwa v205, v93 dst_sel:DWORD dst_unused:UNUSED_PAD src0_sel:WORD_1
	v_cvt_f32_f16_e32 v241, v94
	v_cvt_f32_f16_sdwa v240, v94 dst_sel:DWORD dst_unused:UNUSED_PAD src0_sel:WORD_1
	v_cvt_f32_f16_e32 v239, v95
	v_cvt_f32_f16_sdwa v238, v95 dst_sel:DWORD dst_unused:UNUSED_PAD src0_sel:WORD_1
	global_load_dwordx4 v[92:95], v160, s[60:61] offset:2096
	global_load_dwordx4 v[100:103], v160, s[60:61] offset:2080
	global_load_dwordx4 v[112:115], v160, s[60:61] offset:2064
	global_load_dwordx4 v[128:131], v160, s[60:61] offset:2048
	v_cvt_f32_f16_e32 v235, v104
	v_cvt_f32_f16_sdwa v233, v104 dst_sel:DWORD dst_unused:UNUSED_PAD src0_sel:WORD_1
	v_cvt_f32_f16_e32 v108, v84
	v_cvt_f32_f16_e32 v104, v96
	s_add_u32 s68, s70, s58
	s_addc_u32 s69, s71, s59
	v_cvt_f32_f16_sdwa v196, v96 dst_sel:DWORD dst_unused:UNUSED_PAD src0_sel:WORD_1
	v_sub_f32_e32 v96, v104, v108
	v_cvt_f32_f16_e32 v231, v105
	v_cvt_f32_f16_sdwa v228, v105 dst_sel:DWORD dst_unused:UNUSED_PAD src0_sel:WORD_1
	v_cvt_f32_f16_e32 v226, v106
	v_cvt_f32_f16_sdwa v210, v106 dst_sel:DWORD dst_unused:UNUSED_PAD src0_sel:WORD_1
	v_cvt_f32_f16_e32 v208, v107
	v_cvt_f32_f16_sdwa v206, v107 dst_sel:DWORD dst_unused:UNUSED_PAD src0_sel:WORD_1
	v_cvt_f32_f16_e32 v201, v97
	v_cvt_f32_f16_sdwa v204, v97 dst_sel:DWORD dst_unused:UNUSED_PAD src0_sel:WORD_1
	v_cvt_f32_f16_e32 v203, v98
	v_cvt_f32_f16_sdwa v198, v98 dst_sel:DWORD dst_unused:UNUSED_PAD src0_sel:WORD_1
	v_cvt_f32_f16_e32 v195, v99
	v_cvt_f32_f16_sdwa v237, v99 dst_sel:DWORD dst_unused:UNUSED_PAD src0_sel:WORD_1
	s_lshl_b64 s[58:59], s[2:3], 2
	v_add_u32_e32 v35, s33, v149
	s_add_u32 s33, s64, s58
	s_addc_u32 s65, s65, s59
	s_add_u32 s64, s33, s77
	s_addc_u32 s65, s65, 0
	v_lshlrev_b32_e32 v158, 2, v140
	v_sub_f32_e32 v108, v109, v108
	v_cvt_f32_f16_sdwa v199, v84 dst_sel:DWORD dst_unused:UNUSED_PAD src0_sel:WORD_1
	v_cvt_f32_f16_e32 v200, v85
	v_cvt_f32_f16_sdwa v202, v85 dst_sel:DWORD dst_unused:UNUSED_PAD src0_sel:WORD_1
	v_cvt_f32_f16_e32 v197, v86
	v_cvt_f32_f16_sdwa v194, v86 dst_sel:DWORD dst_unused:UNUSED_PAD src0_sel:WORD_1
	v_cvt_f32_f16_e32 v161, v87
	v_cvt_f32_f16_sdwa v193, v87 dst_sel:DWORD dst_unused:UNUSED_PAD src0_sel:WORD_1
	v_cvt_f32_f16_e32 v192, v88
	v_cvt_f32_f16_sdwa v191, v88 dst_sel:DWORD dst_unused:UNUSED_PAD src0_sel:WORD_1
	v_cvt_f32_f16_e32 v190, v89
	v_cvt_f32_f16_sdwa v189, v89 dst_sel:DWORD dst_unused:UNUSED_PAD src0_sel:WORD_1
	v_cvt_f32_f16_e32 v188, v90
	v_cvt_f32_f16_sdwa v187, v90 dst_sel:DWORD dst_unused:UNUSED_PAD src0_sel:WORD_1
	v_cvt_f32_f16_e32 v186, v91
	v_cvt_f32_f16_sdwa v185, v91 dst_sel:DWORD dst_unused:UNUSED_PAD src0_sel:WORD_1
	v_cmp_lt_i32_e32 vcc, v223, v218
	s_add_u32 s33, s66, s58
	s_addc_u32 s58, s67, s59
	s_add_u32 s66, s33, s77
	s_mov_b32 s33, 0xf800000
	s_addc_u32 s67, s58, 0
	v_lshl_add_u32 v35, v35, 14, 0
	v_and_b32_e32 v255, 15, v217
	v_mul_u32_u24_e32 v255, 0x88, v255
	v_lshl_add_u32 v255, v140, 1, v255
	v_add_u32_e32 v255, v35, v255
	s_waitcnt vmcnt(0)
	v_fma_mix_f32 v159, v96, v128, v84 op_sel_hi:[0,0,1]
	global_load_dwordx4 v[96:99], v160, s[68:69] offset:2096
	global_load_dwordx4 v[104:107], v160, s[68:69] offset:2080
	global_load_dwordx4 v[120:123], v160, s[68:69] offset:2064
	global_load_dwordx4 v[132:135], v160, s[68:69] offset:2048
	v_sub_f32_e32 v128, v196, v199
	v_fma_mix_f32 v196, v128, v129, v84 op_sel:[0,0,1] op_sel_hi:[0,0,1]
	v_sub_f32_e32 v128, v201, v200
	v_fma_mix_f32 v201, v128, v130, v85 op_sel_hi:[0,0,1]
	v_sub_f32_e32 v128, v242, v200
	v_sub_f32_e32 v84, v243, v199
	v_sub_f32_e32 v129, v231, v190
	v_sub_f32_e32 v130, v232, v190
	s_waitcnt vmcnt(0)
	v_fmac_f32_e32 v159, v108, v132
	global_load_dwordx4 v[108:111], v158, s[64:65] offset:48
	global_load_dwordx4 v[116:119], v158, s[64:65] offset:32
	global_load_dwordx4 v[124:127], v158, s[64:65] offset:16
	global_load_dwordx4 v[136:139], v158, s[64:65]
	v_fmac_f32_e32 v201, v128, v134
	v_sub_f32_e32 v128, v204, v202
	v_fma_mix_f32 v204, v128, v131, v85 op_sel:[0,0,1] op_sel_hi:[0,0,1]
	v_sub_f32_e32 v85, v205, v202
	v_fmac_f32_e32 v204, v85, v135
	v_sub_f32_e32 v85, v203, v197
	v_fmac_f32_e32 v196, v84, v133
	v_fma_mix_f32 v202, v85, v112, v86 op_sel_hi:[0,0,1]
	v_sub_f32_e32 v85, v241, v197
	v_fmac_f32_e32 v202, v85, v120
	v_sub_f32_e32 v85, v198, v194
	v_fma_mix_f32 v197, v85, v113, v86 op_sel:[0,0,1] op_sel_hi:[0,0,1]
	v_sub_f32_e32 v85, v240, v194
	v_fmac_f32_e32 v197, v85, v121
	v_sub_f32_e32 v85, v195, v161
	v_fma_mix_f32 v194, v85, v114, v87 op_sel_hi:[0,0,1]
	v_sub_f32_e32 v85, v239, v161
	v_fmac_f32_e32 v194, v85, v122
	v_sub_f32_e32 v85, v237, v193
	v_fma_mix_f32 v161, v85, v115, v87 op_sel:[0,0,1] op_sel_hi:[0,0,1]
	v_sub_f32_e32 v85, v238, v193
	v_sub_f32_e32 v134, v235, v192
	v_fmac_f32_e32 v161, v85, v123
	v_fma_mix_f32 v85, v134, v100, v88 op_sel_hi:[0,0,1]
	v_sub_f32_e32 v133, v236, v192
	v_fmac_f32_e32 v85, v133, v104
	v_sub_f32_e32 v131, v233, v191
	v_sub_f32_e32 v132, v234, v191
	v_sub_f32_e32 v128, v230, v189
	v_sub_f32_e32 v123, v210, v187
	v_sub_f32_e32 v121, v208, v186
	v_sub_f32_e32 v122, v211, v186
	v_sub_f32_e32 v120, v209, v185
	v_cvt_f32_f16_e32 v104, v68
	v_lshl_add_u32 v135, v141, 1, v35
	s_waitcnt vmcnt(2)
	v_mul_f32_e32 v85, v116, v85
	s_waitcnt vmcnt(1)
	v_mul_f32_e32 v203, v124, v202
	s_waitcnt vmcnt(0)
	v_mul_f32_e32 v199, v137, v196
	v_mul_f32_e32 v207, v136, v159
	v_mul_f32_e32 v84, v199, v199
	v_fmac_f32_e32 v84, v207, v207
	v_mul_f32_e32 v200, v138, v201
	v_fmac_f32_e32 v84, v200, v200
	v_mul_f32_e32 v205, v139, v204
	v_fmac_f32_e32 v84, v205, v205
	v_fmac_f32_e32 v84, v203, v203
	v_mul_f32_e32 v198, v125, v197
	v_fmac_f32_e32 v84, v198, v198
	v_mul_f32_e32 v195, v126, v194
	v_fmac_f32_e32 v84, v195, v195
	v_mul_f32_e32 v193, v127, v161
	v_fmac_f32_e32 v84, v193, v193
	v_fmac_f32_e32 v84, v85, v85
	v_fma_mix_f32 v85, v131, v101, v88 op_sel:[0,0,1] op_sel_hi:[0,0,1]
	v_fmac_f32_e32 v85, v132, v105
	v_mul_f32_e32 v85, v117, v85
	v_fmac_f32_e32 v84, v85, v85
	v_fma_mix_f32 v85, v129, v102, v89 op_sel_hi:[0,0,1]
	v_fmac_f32_e32 v85, v130, v106
	v_mul_f32_e32 v85, v118, v85
	v_sub_f32_e32 v127, v228, v189
	v_fmac_f32_e32 v84, v85, v85
	v_fma_mix_f32 v85, v127, v103, v89 op_sel:[0,0,1] op_sel_hi:[0,0,1]
	v_fmac_f32_e32 v85, v128, v107
	v_mul_f32_e32 v85, v119, v85
	v_sub_f32_e32 v125, v226, v188
	v_fmac_f32_e32 v84, v85, v85
	v_fma_mix_f32 v85, v125, v92, v90 op_sel_hi:[0,0,1]
	v_sub_f32_e32 v126, v229, v188
	v_fmac_f32_e32 v85, v126, v96
	v_mul_f32_e32 v85, v108, v85
	v_fmac_f32_e32 v84, v85, v85
	v_fma_mix_f32 v85, v123, v93, v90 op_sel:[0,0,1] op_sel_hi:[0,0,1]
	v_sub_f32_e32 v124, v227, v187
	v_fmac_f32_e32 v85, v124, v97
	v_mul_f32_e32 v85, v109, v85
	v_fmac_f32_e32 v84, v85, v85
	v_fma_mix_f32 v85, v121, v94, v91 op_sel_hi:[0,0,1]
	v_fmac_f32_e32 v85, v122, v98
	v_mul_f32_e32 v85, v110, v85
	v_sub_f32_e32 v119, v206, v185
	v_fmac_f32_e32 v84, v85, v85
	v_fma_mix_f32 v85, v119, v95, v91 op_sel:[0,0,1] op_sel_hi:[0,0,1]
	v_fmac_f32_e32 v85, v120, v99
	v_mul_f32_e32 v85, v111, v85
	v_fmac_f32_e32 v84, v85, v85
	v_cndmask_b32_e32 v85, v217, v223, vcc
	v_lshlrev_b32_e32 v85, 2, v85
	ds_bpermute_b32 v85, v85, v84
	v_cmp_lt_i32_e32 vcc, v224, v218
	v_cvt_f32_f16_e32 v117, v64
	v_cvt_f32_f16_e32 v116, v72
	v_cvt_f32_f16_e32 v137, v76
	s_waitcnt lgkmcnt(0)
	v_add_f32_e32 v84, v84, v85
	v_cndmask_b32_e32 v85, v217, v224, vcc
	v_lshlrev_b32_e32 v85, 2, v85
	ds_bpermute_b32 v85, v85, v84
	v_sub_f32_e32 v104, v104, v117
	v_add3_u32 v206, v35, v178, v179
	s_waitcnt lgkmcnt(0)
	v_add_f32_e32 v84, v84, v85
	v_cmp_gt_f32_e32 vcc, s33, v84
	v_mul_f32_e32 v85, 0x4f800000, v84
	s_nop 0
	v_cndmask_b32_e32 v84, v84, v85, vcc
	v_sqrt_f32_e32 v85, v84
	s_nop 0
	v_add_u32_e32 v86, -1, v85
	v_fma_f32 v87, -v86, v85, v84
	v_cmp_ge_f32_e64 s[58:59], 0, v87
	v_add_u32_e32 v87, 1, v85
	s_nop 0
	v_cndmask_b32_e64 v86, v85, v86, s[58:59]
	v_fma_f32 v85, -v87, v85, v84
	v_cmp_lt_f32_e64 s[58:59], 0, v85
	s_nop 1
	v_cndmask_b32_e64 v85, v86, v87, s[58:59]
	v_mul_f32_e32 v86, 0x37800000, v85
	v_cndmask_b32_e32 v85, v85, v86, vcc
	v_cmp_class_f32_e32 vcc, v84, v214
	s_nop 1
	v_cndmask_b32_e32 v84, v85, v84, vcc
	v_max_f32_e32 v84, 0x2b8cbccc, v84
	v_rcp_f32_e32 v118, v84
	global_load_dwordx4 v[96:99], v160, s[60:61] offset:16
	global_load_dwordx4 v[84:87], v160, s[60:61]
	global_load_dwordx4 v[92:95], v160, s[68:69] offset:16
	global_load_dwordx4 v[88:91], v160, s[68:69]
	global_load_dwordx4 v[100:103], v181, s[60:61] offset:16
	global_load_dwordx4 v[108:111], v181, s[60:61]
	v_mul_f32_e32 v138, v207, v118
	s_waitcnt vmcnt(0)
	v_fma_mix_f32 v208, v104, v108, v64 op_sel_hi:[0,0,1]
	global_load_dwordx4 v[104:107], v181, s[68:69] offset:16
	global_load_dwordx4 v[112:115], v181, s[68:69]
	v_sub_f32_e32 v108, v116, v117
	v_cvt_f32_f16_e32 v116, v80
	s_waitcnt vmcnt(0)
	global_load_dwordx4 v[18:21], v[18:19], off
	s_and_saveexec_b64 s[84:85], s[98:99]
	global_load_dwordx4 v[22:25], v[22:23], off offset:-3824
	global_load_dwordx4 v[36:39], v[36:37], off offset:-1776
	s_or_b64 exec, exec, s[84:85]
	s_and_saveexec_b64 s[84:85], s[100:101]
	global_load_dwordx4 v[26:29], v[26:27], off offset:3840
	global_load_dwordx4 v[40:43], v[40:41], off offset:1792
	s_or_b64 exec, exec, s[84:85]
	global_load_dwordx4 v[30:33], v[30:31], off
	global_load_dwordx4 v[44:47], v[48:49], off offset:16
	global_load_dwordx4 v[48:51], v[50:51], off offset:16
	s_nop 4
	v_fmac_f32_e32 v208, v108, v112
	v_add_f32_dpp v108, v137, v137 row_shr:1 row_mask:0xf bank_mask:0xf bound_ctrl:1
	v_mul_f32_e32 v112, v138, v116
	v_add_f32_e32 v116, -1.0, v116
	v_add_f32_dpp v108, v108, v108 row_shr:2 row_mask:0xf bank_mask:0xf bound_ctrl:1
	v_fma_f32 v116, v116, v6, 1.0
	v_mul_f32_e32 v139, v159, v116
	v_add_f32_dpp v108, v108, v108 row_shr:4 row_mask:0xf bank_mask:0xf bound_ctrl:1
	v_add_u32_e32 v159, v206, v166
	s_nop 0
	v_add_f32_dpp v136, v108, v108 row_shr:8 row_mask:0xf bank_mask:0xf bound_ctrl:1
	s_nop 1
	v_mov_b32_dpp v108, v136 row_newbcast:15 row_mask:0xf bank_mask:0xf bound_ctrl:1
	v_sub_f32_e32 v116, v136, v108
	v_mul_f32_e32 v116, 0x3fb8aa3b, v116
	v_exp_f32_e32 v116, v116
	s_nop 0
	v_mul_f32_e32 v117, v112, v116
	v_mul_f32_e32 v116, v116, v139
	v_mov_b32_e32 v183, v117
	v_mov_b32_e32 v184, v116
	v_mov_b32_e32 v254, v208
	v_add_u32_e32 v117, v135, v167
	s_and_saveexec_b64 s[58:59], s[40:41]
	s_cbranch_execz .LBB0_333
	v_mul_f32_e32 v108, 0xbfb8aa3b, v108
	v_exp_f32_e32 v108, v108
	v_lshl_add_u32 v116, v140, 2, v35
	ds_write_b32 v116, v108 offset:12800
.LBB0_333:
	s_or_b64 exec, exec, s[58:59]
	v_cvt_f32_f16_sdwa v108, v64 dst_sel:DWORD dst_unused:UNUSED_PAD src0_sel:WORD_1
	v_cvt_f32_f16_sdwa v68, v68 dst_sel:DWORD dst_unused:UNUSED_PAD src0_sel:WORD_1
	v_cvt_f32_f16_sdwa v72, v72 dst_sel:DWORD dst_unused:UNUSED_PAD src0_sel:WORD_1
	v_mov_b32_e32 v159, v34
	v_lshl_add_u64 v[116:117], s[66:67], 0, v[158:159]
	v_sub_f32_e32 v68, v68, v108
	v_fma_mix_f32 v207, v68, v109, v64 op_sel:[0,0,1] op_sel_hi:[0,0,1]
	v_sub_f32_e32 v64, v72, v108
	v_fmac_f32_e32 v207, v64, v113
	v_cvt_f32_f16_sdwa v113, v76 dst_sel:DWORD dst_unused:UNUSED_PAD src0_sel:WORD_1
	v_cvt_f32_f16_sdwa v76, v80 dst_sel:DWORD dst_unused:UNUSED_PAD src0_sel:WORD_1
	v_mul_f32_e32 v80, v199, v118
	v_add_u32_e32 v109, v206, v168
	v_add_f32_dpp v64, v113, v113 row_shr:1 row_mask:0xf bank_mask:0xf bound_ctrl:1
	s_nop 1
	v_add_f32_dpp v64, v64, v64 row_shr:2 row_mask:0xf bank_mask:0xf bound_ctrl:1
	s_nop 1
	v_add_f32_dpp v64, v64, v64 row_shr:4 row_mask:0xf bank_mask:0xf bound_ctrl:1
	s_nop 1
	v_add_f32_dpp v68, v64, v64 row_shr:8 row_mask:0xf bank_mask:0xf bound_ctrl:1
	v_mul_f32_e32 v64, v80, v76
	v_add_f32_e32 v76, -1.0, v76
	v_mov_b32_dpp v72, v68 row_newbcast:15 row_mask:0xf bank_mask:0xf bound_ctrl:1
	v_fma_f32 v76, v76, v7, 1.0
	v_mul_f32_e32 v196, v196, v76
	v_sub_f32_e32 v76, v68, v72
	v_mul_f32_e32 v76, 0x3fb8aa3b, v76
	v_exp_f32_e32 v76, v76
	s_nop 0
	v_mul_f32_e32 v108, v64, v76
	v_mul_f32_e32 v76, v76, v196
	v_cvt_pk_bf16_f32 v2, v183, v108
	v_cvt_pk_bf16_f32 v4, v184, v76
	v_cvt_pk_bf16_f32 v152, v254, v207
	v_add_u32_e32 v108, v135, v169
	s_and_saveexec_b64 s[58:59], s[40:41]
	s_cbranch_execz .LBB0_335
	v_mul_f32_e32 v72, 0xbfb8aa3b, v72
	v_exp_f32_e32 v72, v72
	v_lshl_add_u32 v76, v140, 2, v35
	ds_write_b32 v76, v72 offset:12804
.LBB0_335:
	s_or_b64 exec, exec, s[58:59]
	v_cvt_f32_f16_e32 v72, v65
	v_cvt_f32_f16_e32 v76, v69
	v_cvt_f32_f16_e32 v199, v73
	v_cvt_f32_f16_e32 v206, v81
	v_mul_f32_e32 v200, v200, v118
	v_sub_f32_e32 v76, v76, v72
	v_sub_f32_e32 v72, v199, v72
	v_cvt_f32_f16_e32 v199, v77
	v_fma_mix_f32 v76, v76, v110, v65 op_sel_hi:[0,0,1]
	v_fmac_f32_e32 v76, v72, v114
	v_mul_f32_e32 v110, v200, v206
	v_add_f32_dpp v72, v199, v199 row_shr:1 row_mask:0xf bank_mask:0xf bound_ctrl:1
	v_add_f32_e32 v206, -1.0, v206
	v_mov_b32_e32 v254, v76
	v_add_f32_dpp v72, v72, v72 row_shr:2 row_mask:0xf bank_mask:0xf bound_ctrl:1
	v_fma_f32 v206, v206, v8, 1.0
	v_add_f32_dpp v72, v72, v72 row_shr:4 row_mask:0xf bank_mask:0xf bound_ctrl:1
	v_mul_f32_e32 v201, v201, v206
	s_nop 0
	v_add_f32_dpp v114, v72, v72 row_shr:8 row_mask:0xf bank_mask:0xf bound_ctrl:1
	s_nop 1
	v_mov_b32_dpp v72, v114 row_newbcast:15 row_mask:0xf bank_mask:0xf bound_ctrl:1
	v_sub_f32_e32 v206, v114, v72
	v_mul_f32_e32 v206, 0x3fb8aa3b, v206
	v_exp_f32_e32 v206, v206
	s_nop 0
	v_mul_f32_e32 v207, v110, v206
	v_mul_f32_e32 v206, v206, v201
	v_mov_b32_e32 v183, v207
	v_mov_b32_e32 v184, v206
	s_and_saveexec_b64 s[58:59], s[40:41]
	s_cbranch_execz .LBB0_337
	v_mul_f32_e32 v72, 0xbfb8aa3b, v72
	v_exp_f32_e32 v72, v72
	v_lshl_add_u32 v76, v140, 2, v35
	ds_write_b32 v76, v72 offset:12808
.LBB0_337:
	s_or_b64 exec, exec, s[58:59]
	v_cvt_f32_f16_sdwa v72, v65 dst_sel:DWORD dst_unused:UNUSED_PAD src0_sel:WORD_1
	v_cvt_f32_f16_sdwa v69, v69 dst_sel:DWORD dst_unused:UNUSED_PAD src0_sel:WORD_1
	v_cvt_f32_f16_sdwa v73, v73 dst_sel:DWORD dst_unused:UNUSED_PAD src0_sel:WORD_1
	v_sub_f32_e32 v69, v69, v72
	v_fma_mix_f32 v76, v69, v111, v65 op_sel:[0,0,1] op_sel_hi:[0,0,1]
	v_cvt_f32_f16_sdwa v111, v77 dst_sel:DWORD dst_unused:UNUSED_PAD src0_sel:WORD_1
	v_sub_f32_e32 v65, v73, v72
	v_cvt_f32_f16_sdwa v73, v81 dst_sel:DWORD dst_unused:UNUSED_PAD src0_sel:WORD_1
	v_fmac_f32_e32 v76, v65, v115
	v_add_f32_dpp v65, v111, v111 row_shr:1 row_mask:0xf bank_mask:0xf bound_ctrl:1
	v_mul_f32_e32 v81, v205, v118
	s_nop 0
	v_add_f32_dpp v65, v65, v65 row_shr:2 row_mask:0xf bank_mask:0xf bound_ctrl:1
	s_nop 1
	v_add_f32_dpp v65, v65, v65 row_shr:4 row_mask:0xf bank_mask:0xf bound_ctrl:1
	s_nop 1
	v_add_f32_dpp v69, v65, v65 row_shr:8 row_mask:0xf bank_mask:0xf bound_ctrl:1
	v_mul_f32_e32 v65, v81, v73
	v_add_f32_e32 v73, -1.0, v73
	v_mov_b32_dpp v72, v69 row_newbcast:15 row_mask:0xf bank_mask:0xf bound_ctrl:1
	v_fma_f32 v73, v73, v9, 1.0
	v_mul_f32_e32 v115, v204, v73
	v_sub_f32_e32 v73, v69, v72
	v_mul_f32_e32 v73, 0x3fb8aa3b, v73
	v_exp_f32_e32 v73, v73
	s_nop 0
	v_mul_f32_e32 v77, v65, v73
	v_mul_f32_e32 v73, v73, v115
	v_cvt_pk_bf16_f32 v5, v184, v73
	v_cvt_pk_bf16_f32 v3, v183, v77
	v_cvt_pk_bf16_f32 v153, v254, v76
	ds_write_b64 v255, v[2:3] offset:4608
	ds_write_b64 v255, v[4:5] offset:6784
	ds_write_b64 v255, v[152:153] offset:9728
	s_and_saveexec_b64 s[58:59], s[40:41]
	s_cbranch_execz .LBB0_339
	v_mul_f32_e32 v72, 0xbfb8aa3b, v72
	v_exp_f32_e32 v72, v72
	v_lshl_add_u32 v73, v140, 2, v35
	ds_write_b32 v73, v72 offset:12812
.LBB0_339:
	s_or_b64 exec, exec, s[58:59]
	v_cvt_f32_f16_e32 v72, v66
	v_cvt_f32_f16_e32 v73, v70
	v_cvt_f32_f16_e32 v76, v74
	v_cvt_f32_f16_e32 v205, v78
	v_mul_f32_e32 v203, v203, v118
	v_sub_f32_e32 v73, v73, v72
	v_fma_mix_f32 v73, v73, v100, v66 op_sel_hi:[0,0,1]
	v_sub_f32_e32 v72, v76, v72
	v_cvt_f32_f16_e32 v76, v82
	v_fmac_f32_e32 v73, v72, v104
	v_add_f32_dpp v72, v205, v205 row_shr:1 row_mask:0xf bank_mask:0xf bound_ctrl:1
	v_mov_b32_e32 v254, v73
	v_mul_f32_e32 v104, v203, v76
	v_add_f32_dpp v72, v72, v72 row_shr:2 row_mask:0xf bank_mask:0xf bound_ctrl:1
	v_add_f32_e32 v76, -1.0, v76
	v_fma_f32 v76, v76, v10, 1.0
	v_add_f32_dpp v72, v72, v72 row_shr:4 row_mask:0xf bank_mask:0xf bound_ctrl:1
	v_mul_f32_e32 v202, v202, v76
	s_nop 0
	v_add_f32_dpp v204, v72, v72 row_shr:8 row_mask:0xf bank_mask:0xf bound_ctrl:1
	s_nop 1
	v_mov_b32_dpp v72, v204 row_newbcast:15 row_mask:0xf bank_mask:0xf bound_ctrl:1
	v_sub_f32_e32 v76, v204, v72
	v_mul_f32_e32 v76, 0x3fb8aa3b, v76
	v_exp_f32_e32 v76, v76
	s_nop 0
	v_mul_f32_e32 v77, v104, v76
	v_mul_f32_e32 v76, v76, v202
	v_mov_b32_e32 v183, v77
	v_mov_b32_e32 v184, v76
	s_and_saveexec_b64 s[58:59], s[40:41]
	s_cbranch_execz .LBB0_341
	v_mul_f32_e32 v72, 0xbfb8aa3b, v72
	v_exp_f32_e32 v72, v72
	v_lshl_add_u32 v73, v140, 2, v35
	ds_write_b32 v73, v72 offset:12816
.LBB0_341:
	s_or_b64 exec, exec, s[58:59]
	v_cvt_f32_f16_sdwa v72, v66 dst_sel:DWORD dst_unused:UNUSED_PAD src0_sel:WORD_1
	v_cvt_f32_f16_sdwa v70, v70 dst_sel:DWORD dst_unused:UNUSED_PAD src0_sel:WORD_1
	v_cvt_f32_f16_sdwa v73, v74 dst_sel:DWORD dst_unused:UNUSED_PAD src0_sel:WORD_1
	v_cvt_f32_f16_sdwa v74, v78 dst_sel:DWORD dst_unused:UNUSED_PAD src0_sel:WORD_1
	v_mul_f32_e32 v78, v198, v118
	v_sub_f32_e32 v70, v70, v72
	v_fma_mix_f32 v76, v70, v101, v66 op_sel:[0,0,1] op_sel_hi:[0,0,1]
	v_sub_f32_e32 v66, v73, v72
	v_cvt_f32_f16_sdwa v73, v82 dst_sel:DWORD dst_unused:UNUSED_PAD src0_sel:WORD_1
	v_fmac_f32_e32 v76, v66, v105
	v_add_f32_dpp v66, v74, v74 row_shr:1 row_mask:0xf bank_mask:0xf bound_ctrl:1
	s_nop 1
	v_add_f32_dpp v66, v66, v66 row_shr:2 row_mask:0xf bank_mask:0xf bound_ctrl:1
	s_nop 1
	v_add_f32_dpp v66, v66, v66 row_shr:4 row_mask:0xf bank_mask:0xf bound_ctrl:1
	s_nop 1
	v_add_f32_dpp v70, v66, v66 row_shr:8 row_mask:0xf bank_mask:0xf bound_ctrl:1
	v_mul_f32_e32 v66, v78, v73
	v_add_f32_e32 v73, -1.0, v73
	v_mov_b32_dpp v72, v70 row_newbcast:15 row_mask:0xf bank_mask:0xf bound_ctrl:1
	v_fma_f32 v73, v73, v11, 1.0
	v_mul_f32_e32 v82, v197, v73
	v_sub_f32_e32 v73, v70, v72
	v_mul_f32_e32 v73, 0x3fb8aa3b, v73
	v_exp_f32_e32 v73, v73
	s_nop 0
	v_mul_f32_e32 v77, v66, v73
	v_mul_f32_e32 v73, v73, v82
	v_cvt_pk_bf16_f32 v4, v184, v73
	v_cvt_pk_bf16_f32 v2, v183, v77
	v_cvt_pk_bf16_f32 v152, v254, v76
	s_and_saveexec_b64 s[58:59], s[40:41]
	s_cbranch_execz .LBB0_343
	v_mul_f32_e32 v72, 0xbfb8aa3b, v72
	v_exp_f32_e32 v72, v72
	v_lshl_add_u32 v73, v140, 2, v35
	ds_write_b32 v73, v72 offset:12820
.LBB0_343:
	s_or_b64 exec, exec, s[58:59]
	v_cvt_f32_f16_e32 v72, v67
	v_cvt_f32_f16_e32 v73, v71
	v_cvt_f32_f16_e32 v76, v75
	v_mul_f32_e32 v195, v195, v118
	v_sub_f32_e32 v73, v73, v72
	v_fma_mix_f32 v73, v73, v102, v67 op_sel_hi:[0,0,1]
	v_sub_f32_e32 v72, v76, v72
	v_fmac_f32_e32 v73, v72, v106
	v_cvt_f32_f16_e32 v106, v79
	v_cvt_f32_f16_e32 v76, v83
	v_mov_b32_e32 v254, v73
	v_add_f32_dpp v72, v106, v106 row_shr:1 row_mask:0xf bank_mask:0xf bound_ctrl:1
	v_mul_f32_e32 v102, v195, v76
	s_nop 0
	v_add_f32_dpp v72, v72, v72 row_shr:2 row_mask:0xf bank_mask:0xf bound_ctrl:1
	v_add_f32_e32 v76, -1.0, v76
	v_fma_f32 v76, v76, v12, 1.0
	v_add_f32_dpp v72, v72, v72 row_shr:4 row_mask:0xf bank_mask:0xf bound_ctrl:1
	v_mul_f32_e32 v194, v194, v76
	s_nop 0
	v_add_f32_dpp v105, v72, v72 row_shr:8 row_mask:0xf bank_mask:0xf bound_ctrl:1
	s_nop 1
	v_mov_b32_dpp v72, v105 row_newbcast:15 row_mask:0xf bank_mask:0xf bound_ctrl:1
	v_sub_f32_e32 v76, v105, v72
	v_mul_f32_e32 v76, 0x3fb8aa3b, v76
	v_exp_f32_e32 v76, v76
	s_nop 0
	v_mul_f32_e32 v77, v102, v76
	v_mul_f32_e32 v76, v76, v194
	v_mov_b32_e32 v183, v77
	v_mov_b32_e32 v184, v76
	s_and_saveexec_b64 s[58:59], s[40:41]
	s_cbranch_execz .LBB0_345
	v_mul_f32_e32 v72, 0xbfb8aa3b, v72
	v_exp_f32_e32 v72, v72
	v_lshl_add_u32 v73, v140, 2, v35
	ds_write_b32 v73, v72 offset:12824
.LBB0_345:
	s_or_b64 exec, exec, s[58:59]
	v_cvt_f32_f16_sdwa v72, v67 dst_sel:DWORD dst_unused:UNUSED_PAD src0_sel:WORD_1
	v_cvt_f32_f16_sdwa v71, v71 dst_sel:DWORD dst_unused:UNUSED_PAD src0_sel:WORD_1
	v_cvt_f32_f16_sdwa v73, v75 dst_sel:DWORD dst_unused:UNUSED_PAD src0_sel:WORD_1
	v_cvt_f32_f16_sdwa v75, v79 dst_sel:DWORD dst_unused:UNUSED_PAD src0_sel:WORD_1
	v_mul_f32_e32 v79, v193, v118
	v_sub_f32_e32 v71, v71, v72
	v_fma_mix_f32 v76, v71, v103, v67 op_sel:[0,0,1] op_sel_hi:[0,0,1]
	v_sub_f32_e32 v67, v73, v72
	v_cvt_f32_f16_sdwa v73, v83 dst_sel:DWORD dst_unused:UNUSED_PAD src0_sel:WORD_1
	v_fmac_f32_e32 v76, v67, v107
	v_add_f32_dpp v67, v75, v75 row_shr:1 row_mask:0xf bank_mask:0xf bound_ctrl:1
	s_nop 1
	v_add_f32_dpp v67, v67, v67 row_shr:2 row_mask:0xf bank_mask:0xf bound_ctrl:1
	s_nop 1
	v_add_f32_dpp v67, v67, v67 row_shr:4 row_mask:0xf bank_mask:0xf bound_ctrl:1
	s_nop 1
	v_add_f32_dpp v71, v67, v67 row_shr:8 row_mask:0xf bank_mask:0xf bound_ctrl:1
	v_mul_f32_e32 v67, v79, v73
	v_add_f32_e32 v73, -1.0, v73
	v_mov_b32_dpp v72, v71 row_newbcast:15 row_mask:0xf bank_mask:0xf bound_ctrl:1
	v_fma_f32 v73, v73, v13, 1.0
	v_mul_f32_e32 v83, v161, v73
	v_sub_f32_e32 v73, v71, v72
	v_mul_f32_e32 v73, 0x3fb8aa3b, v73
	v_exp_f32_e32 v73, v73
	s_nop 0
	v_mul_f32_e32 v77, v67, v73
	v_mul_f32_e32 v73, v73, v83
	v_cvt_pk_bf16_f32 v5, v184, v73
	v_cvt_pk_bf16_f32 v3, v183, v77
	v_cvt_pk_bf16_f32 v153, v254, v76
	ds_write_b64 v255, v[2:3] offset:4616
	ds_write_b64 v255, v[4:5] offset:6792
	ds_write_b64 v255, v[152:153] offset:9736
	s_and_saveexec_b64 s[58:59], s[40:41]
	s_cbranch_execz .LBB0_347
	v_mul_f32_e32 v72, 0xbfb8aa3b, v72
	v_exp_f32_e32 v72, v72
	v_lshl_add_u32 v73, v140, 2, v35
	ds_write_b32 v73, v72 offset:12828
.LBB0_347:
	s_or_b64 exec, exec, s[58:59]
	v_cvt_f32_f16_sdwa v103, v55 dst_sel:DWORD dst_unused:UNUSED_PAD src0_sel:WORD_1
	v_cvt_f32_f16_sdwa v107, v59 dst_sel:DWORD dst_unused:UNUSED_PAD src0_sel:WORD_1
	v_lshl_add_u64 v[100:101], s[64:65], 0, v[158:159]
	v_cvt_f32_f16_sdwa v158, v63 dst_sel:DWORD dst_unused:UNUSED_PAD src0_sel:WORD_1
	v_sub_f32_e32 v75, v75, v71
	v_sub_f32_e32 v107, v107, v103
	v_fma_mix_f32 v99, v107, v99, v55 op_sel:[0,0,1] op_sel_hi:[0,0,1]
	v_sub_f32_e32 v103, v158, v103
	v_fmac_f32_e32 v99, v103, v95
	v_mul_f32_e32 v95, 0x3fb8aa3b, v71
	v_mul_f32_e32 v75, 0x3fb8aa3b, v75
	v_exp_f32_e32 v95, v95
	v_exp_f32_e32 v75, v75
	v_cvt_f32_f16_e32 v59, v59
	v_cvt_f32_f16_e32 v63, v63
	v_mul_f32_e32 v67, v67, v95
	v_mul_f32_e32 v75, v79, v75
	v_mul_f32_e32 v79, v95, v83
	v_cvt_f32_f16_e32 v83, v55
	v_cvt_f32_f16_sdwa v95, v58 dst_sel:DWORD dst_unused:UNUSED_PAD src0_sel:WORD_1
	v_sub_f32_e32 v74, v74, v70
	v_mul_f32_e32 v74, 0x3fb8aa3b, v74
	v_sub_f32_e32 v59, v59, v83
	v_fma_mix_f32 v55, v59, v98, v55 op_sel_hi:[0,0,1]
	v_sub_f32_e32 v59, v63, v83
	v_mul_f32_e32 v83, 0xbfb8aa3b, v105
	v_exp_f32_e32 v83, v83
	v_fmac_f32_e32 v55, v59, v94
	v_cvt_f32_f16_sdwa v98, v62 dst_sel:DWORD dst_unused:UNUSED_PAD src0_sel:WORD_1
	v_exp_f32_e32 v74, v74
	v_mul_f32_e32 v83, v55, v83
	v_cvt_f32_f16_sdwa v55, v54 dst_sel:DWORD dst_unused:UNUSED_PAD src0_sel:WORD_1
	v_cvt_f32_f16_e32 v58, v58
	v_mul_f32_e32 v74, v78, v74
	v_cvt_f32_f16_e32 v62, v62
	v_sub_f32_e32 v95, v95, v55
	v_fma_mix_f32 v95, v95, v97, v54 op_sel:[0,0,1] op_sel_hi:[0,0,1]
	v_sub_f32_e32 v55, v98, v55
	v_fmac_f32_e32 v95, v55, v93
	v_mul_f32_e32 v55, 0x3fb8aa3b, v70
	v_exp_f32_e32 v55, v55
	v_cvt_f32_f16_sdwa v93, v61 dst_sel:DWORD dst_unused:UNUSED_PAD src0_sel:WORD_1
	v_mul_f32_e32 v59, 0x3fb8aa3b, v105
	v_exp_f32_e32 v59, v59
	v_mul_f32_e32 v66, v66, v55
	v_mul_f32_e32 v78, v55, v82
	v_cvt_f32_f16_e32 v55, v54
	v_mul_f32_e32 v94, v102, v59
	v_sub_f32_e32 v63, v106, v105
	v_mul_f32_e32 v63, 0x3fb8aa3b, v63
	v_sub_f32_e32 v58, v58, v55
	v_fma_mix_f32 v54, v58, v96, v54 op_sel_hi:[0,0,1]
	v_sub_f32_e32 v55, v62, v55
	v_fmac_f32_e32 v54, v55, v92
	v_mul_f32_e32 v55, 0x3fb8aa3b, v204
	v_mul_f32_e32 v62, 0xbfb8aa3b, v204
	v_exp_f32_e32 v55, v55
	v_exp_f32_e32 v62, v62
	v_sub_f32_e32 v58, v205, v204
	v_mul_f32_e32 v58, 0x3fb8aa3b, v58
	v_mul_f32_e32 v82, v104, v55
	v_mul_f32_e32 v62, v54, v62
	v_mul_f32_e32 v92, v55, v202
	v_cvt_f32_f16_sdwa v54, v53 dst_sel:DWORD dst_unused:UNUSED_PAD src0_sel:WORD_1
	v_cvt_f32_f16_sdwa v55, v57 dst_sel:DWORD dst_unused:UNUSED_PAD src0_sel:WORD_1
	v_mul_f32_e32 v71, 0xbfb8aa3b, v71
	v_exp_f32_e32 v63, v63
	v_mul_f32_e32 v70, 0xbfb8aa3b, v70
	v_sub_f32_e32 v55, v55, v54
	v_fma_mix_f32 v55, v55, v87, v53 op_sel:[0,0,1] op_sel_hi:[0,0,1]
	v_sub_f32_e32 v54, v93, v54
	v_sub_f32_e32 v87, v111, v69
	v_fmac_f32_e32 v55, v54, v91
	v_mul_f32_e32 v54, 0x3fb8aa3b, v69
	v_mul_f32_e32 v87, 0x3fb8aa3b, v87
	v_mul_f32_e32 v69, 0xbfb8aa3b, v69
	v_exp_f32_e32 v54, v54
	v_exp_f32_e32 v87, v87
	v_exp_f32_e32 v69, v69
	v_exp_f32_e32 v58, v58
	v_mul_f32_e32 v65, v65, v54
	v_mul_f32_e32 v81, v81, v87
	v_mul_f32_e32 v69, v55, v69
	v_mul_f32_e32 v87, v54, v115
	v_cvt_f32_f16_e32 v54, v53
	v_cvt_f32_f16_e32 v55, v57
	v_cvt_f32_f16_e32 v57, v61
	v_exp_f32_e32 v71, v71
	v_exp_f32_e32 v70, v70
	v_sub_f32_e32 v55, v55, v54
	v_fma_mix_f32 v53, v55, v86, v53 op_sel_hi:[0,0,1]
	v_sub_f32_e32 v54, v57, v54
	v_fmac_f32_e32 v53, v54, v90
	v_mul_f32_e32 v54, 0x3fb8aa3b, v114
	v_mul_f32_e32 v57, 0xbfb8aa3b, v114
	v_exp_f32_e32 v54, v54
	v_exp_f32_e32 v57, v57
	v_cvt_f32_f16_sdwa v90, v60 dst_sel:DWORD dst_unused:UNUSED_PAD src0_sel:WORD_1
	v_sub_f32_e32 v55, v199, v114
	v_mul_f32_e32 v61, v110, v54
	v_mul_f32_e32 v57, v53, v57
	v_mul_f32_e32 v86, v54, v201
	v_cvt_f32_f16_sdwa v53, v52 dst_sel:DWORD dst_unused:UNUSED_PAD src0_sel:WORD_1
	v_cvt_f32_f16_sdwa v54, v56 dst_sel:DWORD dst_unused:UNUSED_PAD src0_sel:WORD_1
	v_mul_f32_e32 v55, 0x3fb8aa3b, v55
	v_exp_f32_e32 v55, v55
	v_mul_f32_e32 v63, v195, v63
	v_sub_f32_e32 v54, v54, v53
	v_fma_mix_f32 v54, v54, v85, v52 op_sel:[0,0,1] op_sel_hi:[0,0,1]
	v_sub_f32_e32 v53, v90, v53
	v_fmac_f32_e32 v54, v53, v89
	v_mul_f32_e32 v53, 0x3fb8aa3b, v68
	v_sub_f32_e32 v85, v113, v68
	v_mul_f32_e32 v68, 0xbfb8aa3b, v68
	v_mul_f32_e32 v85, 0x3fb8aa3b, v85
	v_exp_f32_e32 v68, v68
	v_exp_f32_e32 v53, v53
	v_exp_f32_e32 v85, v85
	v_mul_f32_e32 v58, v203, v58
	v_mul_f32_e32 v68, v54, v68
	v_cvt_f32_f16_e32 v54, v56
	v_cvt_f32_f16_e32 v56, v52
	v_mul_f32_e32 v80, v80, v85
	v_mul_f32_e32 v64, v64, v53
	v_mul_f32_e32 v85, v53, v196
	v_lshlrev_b32_e32 v53, 1, v140
	v_add3_u32 v102, v135, v171, v53
	v_cvt_f32_f16_e32 v53, v60
	v_sub_f32_e32 v54, v54, v56
	v_fma_mix_f32 v52, v54, v84, v52 op_sel_hi:[0,0,1]
	v_sub_f32_e32 v54, v137, v136
	v_sub_f32_e32 v53, v53, v56
	v_mul_f32_e32 v54, 0x3fb8aa3b, v54
	v_fmac_f32_e32 v52, v53, v88
	v_mul_f32_e32 v53, 0x3fb8aa3b, v136
	v_exp_f32_e32 v54, v54
	v_mul_f32_e32 v56, 0xbfb8aa3b, v136
	v_exp_f32_e32 v53, v53
	v_exp_f32_e32 v56, v56
	v_mul_f32_e32 v55, v200, v55
	v_mul_f32_e32 v54, v138, v54
	v_mul_f32_e32 v71, v99, v71
	v_mul_f32_e32 v70, v95, v70
	v_mul_f32_e32 v56, v52, v56
	v_mul_f32_e32 v60, v112, v53
	v_mul_f32_e32 v84, v53, v139
	v_cvt_pk_bf16_f32 v52, v54, v80
	v_cvt_pk_bf16_f32 v53, v55, v81
	v_cvt_pk_bf16_f32 v54, v58, v74
	v_cvt_pk_bf16_f32 v55, v63, v75
	ds_write_b128 v102, v[52:55]
	v_cvt_pk_bf16_f32 v52, v56, v68
	v_cvt_pk_bf16_f32 v53, v57, v69
	v_cvt_pk_bf16_f32 v54, v62, v70
	v_cvt_pk_bf16_f32 v55, v83, v71
	v_mov_b32_e32 v161, v34
	v_mul_f32_e32 v59, v59, v194
	ds_write_b128 v102, v[52:55] offset:2304
	v_cvt_pk_bf16_f32 v52, v60, v64
	v_cvt_pk_bf16_f32 v53, v61, v65
	v_cvt_pk_bf16_f32 v54, v82, v66
	v_cvt_pk_bf16_f32 v55, v94, v67
	v_lshl_add_u64 v[72:73], s[60:61], 0, v[160:161]
	v_lshl_add_u64 v[76:77], s[68:69], 0, v[160:161]
	ds_write_b128 v162, v[52:55]
	v_cvt_pk_bf16_f32 v52, v84, v85
	v_cvt_pk_bf16_f32 v53, v86, v87
	v_cvt_pk_bf16_f32 v54, v92, v78
	v_cvt_pk_bf16_f32 v55, v59, v79
	ds_write_b128 v162, v[52:55] offset:2304
	global_load_dwordx4 v[64:67], v[72:73], off offset:48
	global_load_dwordx4 v[56:59], v[72:73], off offset:32
	global_load_dwordx4 v[60:63], v[76:77], off offset:48
	global_load_dwordx4 v[52:55], v[76:77], off offset:32
	global_load_dwordx4 v[68:71], v[72:73], off offset:2096
	global_load_dwordx4 v[84:87], v[72:73], off offset:2080
	s_nop 0
	global_load_dwordx4 v[72:75], v[76:77], off offset:2096
	global_load_dwordx4 v[88:91], v[76:77], off offset:2080
	s_nop 0
	global_load_dwordx4 v[76:79], v182, s[60:61] offset:16
	global_load_dwordx4 v[92:95], v182, s[60:61]
	s_waitcnt vmcnt(10)
	v_cvt_f32_f16_e32 v80, v36
	v_cvt_f32_f16_e32 v103, v48
	s_waitcnt vmcnt(4)
	v_fmac_f32_e32 v192, v134, v84
	s_waitcnt vmcnt(2)
	v_fmac_f32_e32 v192, v133, v88
	v_cvt_f32_f16_e32 v88, v30
	v_cvt_f32_f16_e32 v84, v40
	v_sub_f32_e32 v80, v80, v88
	s_waitcnt vmcnt(0)
	v_fma_mix_f32 v105, v80, v92, v30 op_sel_hi:[0,0,1]
	global_load_dwordx4 v[80:83], v182, s[68:69] offset:16
	global_load_dwordx4 v[96:99], v182, s[68:69]
	v_sub_f32_e32 v84, v84, v88
	v_cvt_f32_f16_e32 v88, v44
	s_waitcnt vmcnt(0)
	v_fmac_f32_e32 v105, v84, v96
	v_add_f32_dpp v84, v88, v88 row_shr:1 row_mask:0xf bank_mask:0xf bound_ctrl:1
	v_mov_b32_e32 v254, v105
	s_nop 0
	v_add_f32_dpp v84, v84, v84 row_shr:2 row_mask:0xf bank_mask:0xf bound_ctrl:1
	s_nop 1
	v_add_f32_dpp v84, v84, v84 row_shr:4 row_mask:0xf bank_mask:0xf bound_ctrl:1
	s_nop 1
	v_add_f32_dpp v92, v84, v84 row_shr:8 row_mask:0xf bank_mask:0xf bound_ctrl:1
	s_waitcnt vmcnt(0)
	v_mul_f32_e32 v84, v192, v246
	v_mul_f32_e32 v96, v118, v84
	v_mov_b32_dpp v104, v92 row_newbcast:15 row_mask:0xf bank_mask:0xf bound_ctrl:1
	v_mul_f32_e32 v84, v96, v103
	v_add_f32_e32 v103, -1.0, v103
	v_fma_f32 v103, v103, v14, 1.0
	v_sub_f32_e32 v106, v92, v104
	v_mul_f32_e32 v106, 0x3fb8aa3b, v106
	v_exp_f32_e32 v106, v106
	v_mul_f32_e32 v103, v192, v103
	v_mul_f32_e32 v107, v106, v84
	v_mul_f32_e32 v106, v106, v103
	v_mov_b32_e32 v183, v107
	v_mov_b32_e32 v184, v106
	s_and_saveexec_b64 s[58:59], s[40:41]
	s_cbranch_execz .LBB0_349
	v_mul_f32_e32 v104, 0xbfb8aa3b, v104
	v_exp_f32_e32 v104, v104
	v_lshl_add_u32 v105, v140, 2, v35
	ds_write_b32 v105, v104 offset:12832
.LBB0_349:
	s_or_b64 exec, exec, s[58:59]
	v_fmac_f32_e32 v191, v131, v85
	v_cvt_f32_f16_sdwa v85, v30 dst_sel:DWORD dst_unused:UNUSED_PAD src0_sel:WORD_1
	v_cvt_f32_f16_sdwa v36, v36 dst_sel:DWORD dst_unused:UNUSED_PAD src0_sel:WORD_1
	v_cvt_f32_f16_sdwa v40, v40 dst_sel:DWORD dst_unused:UNUSED_PAD src0_sel:WORD_1
	v_fmac_f32_e32 v191, v132, v89
	v_cvt_f32_f16_sdwa v48, v48 dst_sel:DWORD dst_unused:UNUSED_PAD src0_sel:WORD_1
	v_sub_f32_e32 v36, v36, v85
	v_fma_mix_f32 v89, v36, v93, v30 op_sel:[0,0,1] op_sel_hi:[0,0,1]
	v_sub_f32_e32 v30, v40, v85
	v_cvt_f32_f16_sdwa v36, v44 dst_sel:DWORD dst_unused:UNUSED_PAD src0_sel:WORD_1
	v_fmac_f32_e32 v89, v30, v97
	v_cvt_pk_bf16_f32 v152, v254, v89
	v_add_f32_dpp v30, v36, v36 row_shr:1 row_mask:0xf bank_mask:0xf bound_ctrl:1
	s_waitcnt vmcnt(0)
	v_mul_f32_e32 v40, v191, v247
	v_add_f32_dpp v30, v30, v30 row_shr:2 row_mask:0xf bank_mask:0xf bound_ctrl:1
	v_mul_f32_e32 v44, v118, v40
	v_mul_f32_e32 v40, v44, v48
	v_add_f32_dpp v30, v30, v30 row_shr:4 row_mask:0xf bank_mask:0xf bound_ctrl:1
	v_add_f32_e32 v48, -1.0, v48
	s_waitcnt vmcnt(0)
	v_fma_f32 v48, v48, v15, 1.0
	v_add_f32_dpp v30, v30, v30 row_shr:8 row_mask:0xf bank_mask:0xf bound_ctrl:1
	v_mul_f32_e32 v48, v191, v48
	s_nop 0
	v_mov_b32_dpp v85, v30 row_newbcast:15 row_mask:0xf bank_mask:0xf bound_ctrl:1
	v_sub_f32_e32 v93, v30, v85
	v_mul_f32_e32 v93, 0x3fb8aa3b, v93
	v_exp_f32_e32 v93, v93
	s_nop 0
	v_mul_f32_e32 v97, v93, v40
	v_mul_f32_e32 v93, v93, v48
	v_cvt_pk_bf16_f32 v2, v183, v97
	v_cvt_pk_bf16_f32 v4, v184, v93
	s_and_saveexec_b64 s[58:59], s[40:41]
	s_cbranch_execz .LBB0_351
	v_mul_f32_e32 v85, 0xbfb8aa3b, v85
	v_exp_f32_e32 v85, v85
	v_lshl_add_u32 v89, v140, 2, v35
	ds_write_b32 v89, v85 offset:12836
.LBB0_351:
	s_or_b64 exec, exec, s[58:59]
	v_fmac_f32_e32 v190, v129, v86
	v_cvt_f32_f16_e32 v85, v31
	v_cvt_f32_f16_e32 v86, v37
	v_cvt_f32_f16_e32 v89, v41
	v_cvt_f32_f16_e32 v93, v49
	v_fmac_f32_e32 v190, v130, v90
	v_sub_f32_e32 v86, v86, v85
	v_sub_f32_e32 v85, v89, v85
	v_fma_mix_f32 v97, v86, v94, v31 op_sel_hi:[0,0,1]
	v_fmac_f32_e32 v97, v85, v98
	v_cvt_f32_f16_e32 v86, v45
	v_mov_b32_e32 v254, v97
	s_waitcnt vmcnt(0)
	v_mul_f32_e32 v89, v190, v248
	v_add_f32_dpp v85, v86, v86 row_shr:1 row_mask:0xf bank_mask:0xf bound_ctrl:1
	v_mul_f32_e32 v90, v118, v89
	v_mul_f32_e32 v89, v90, v93
	v_add_f32_dpp v85, v85, v85 row_shr:2 row_mask:0xf bank_mask:0xf bound_ctrl:1
	v_add_f32_e32 v93, -1.0, v93
	s_waitcnt vmcnt(0)
	v_fma_f32 v93, v93, v16, 1.0
	v_add_f32_dpp v85, v85, v85 row_shr:4 row_mask:0xf bank_mask:0xf bound_ctrl:1
	v_mul_f32_e32 v93, v190, v93
	s_nop 0
	v_add_f32_dpp v85, v85, v85 row_shr:8 row_mask:0xf bank_mask:0xf bound_ctrl:1
	s_nop 1
	v_mov_b32_dpp v94, v85 row_newbcast:15 row_mask:0xf bank_mask:0xf bound_ctrl:1
	v_sub_f32_e32 v98, v85, v94
	v_mul_f32_e32 v98, 0x3fb8aa3b, v98
	v_exp_f32_e32 v98, v98
	s_nop 0
	v_mul_f32_e32 v104, v98, v89
	v_mul_f32_e32 v98, v98, v93
	v_mov_b32_e32 v183, v104
	v_mov_b32_e32 v184, v98
	s_and_saveexec_b64 s[58:59], s[40:41]
	s_cbranch_execz .LBB0_353
	v_mul_f32_e32 v94, 0xbfb8aa3b, v94
	v_exp_f32_e32 v94, v94
	v_lshl_add_u32 v97, v140, 2, v35
	ds_write_b32 v97, v94 offset:12840
.LBB0_353:
	s_or_b64 exec, exec, s[58:59]
	v_fmac_f32_e32 v189, v127, v87
	v_cvt_f32_f16_sdwa v87, v31 dst_sel:DWORD dst_unused:UNUSED_PAD src0_sel:WORD_1
	v_cvt_f32_f16_sdwa v37, v37 dst_sel:DWORD dst_unused:UNUSED_PAD src0_sel:WORD_1
	v_cvt_f32_f16_sdwa v41, v41 dst_sel:DWORD dst_unused:UNUSED_PAD src0_sel:WORD_1
	v_fmac_f32_e32 v189, v128, v91
	v_sub_f32_e32 v37, v37, v87
	v_fma_mix_f32 v91, v37, v95, v31 op_sel:[0,0,1] op_sel_hi:[0,0,1]
	v_sub_f32_e32 v31, v41, v87
	v_cvt_f32_f16_sdwa v37, v45 dst_sel:DWORD dst_unused:UNUSED_PAD src0_sel:WORD_1
	v_fmac_f32_e32 v91, v31, v99
	v_cvt_f32_f16_sdwa v49, v49 dst_sel:DWORD dst_unused:UNUSED_PAD src0_sel:WORD_1
	v_cvt_pk_bf16_f32 v153, v254, v91
	v_add_f32_dpp v31, v37, v37 row_shr:1 row_mask:0xf bank_mask:0xf bound_ctrl:1
	s_waitcnt vmcnt(0)
	v_mul_f32_e32 v41, v189, v249
	v_add_f32_dpp v31, v31, v31 row_shr:2 row_mask:0xf bank_mask:0xf bound_ctrl:1
	v_mul_f32_e32 v45, v118, v41
	v_mul_f32_e32 v41, v45, v49
	v_add_f32_dpp v31, v31, v31 row_shr:4 row_mask:0xf bank_mask:0xf bound_ctrl:1
	v_add_f32_e32 v49, -1.0, v49
	v_fma_f32 v49, v49, v17, 1.0
	v_add_f32_dpp v31, v31, v31 row_shr:8 row_mask:0xf bank_mask:0xf bound_ctrl:1
	v_mul_f32_e32 v49, v189, v49
	s_nop 0
	v_mov_b32_dpp v87, v31 row_newbcast:15 row_mask:0xf bank_mask:0xf bound_ctrl:1
	v_sub_f32_e32 v94, v31, v87
	v_mul_f32_e32 v94, 0x3fb8aa3b, v94
	v_exp_f32_e32 v94, v94
	s_nop 0
	v_mul_f32_e32 v95, v94, v41
	v_mul_f32_e32 v94, v94, v49
	v_cvt_pk_bf16_f32 v3, v183, v95
	v_cvt_pk_bf16_f32 v5, v184, v94
	ds_write_b64 v255, v[2:3] offset:4624
	ds_write_b64 v255, v[4:5] offset:6800
	ds_write_b64 v255, v[152:153] offset:9744
	s_and_saveexec_b64 s[58:59], s[40:41]
	s_cbranch_execz .LBB0_355
	v_mul_f32_e32 v87, 0xbfb8aa3b, v87
	v_exp_f32_e32 v87, v87
	v_lshl_add_u32 v91, v140, 2, v35
	ds_write_b32 v91, v87 offset:12844
.LBB0_355:
	s_or_b64 exec, exec, s[58:59]
	v_fmac_f32_e32 v188, v125, v68
	v_fmac_f32_e32 v188, v126, v72
	v_cvt_f32_f16_e32 v68, v32
	v_cvt_f32_f16_e32 v72, v38
	v_cvt_f32_f16_e32 v87, v42
	v_sub_f32_e32 v72, v72, v68
	v_fma_mix_f32 v94, v72, v76, v32 op_sel_hi:[0,0,1]
	v_cvt_f32_f16_e32 v72, v46
	v_sub_f32_e32 v68, v87, v68
	v_fmac_f32_e32 v94, v68, v80
	v_cvt_f32_f16_e32 v87, v50
	v_add_f32_dpp v68, v72, v72 row_shr:1 row_mask:0xf bank_mask:0xf bound_ctrl:1
	v_mov_b32_e32 v254, v94
	s_waitcnt vmcnt(0)
	v_mul_f32_e32 v76, v188, v250
	v_add_f32_dpp v68, v68, v68 row_shr:2 row_mask:0xf bank_mask:0xf bound_ctrl:1
	v_mul_f32_e32 v80, v118, v76
	v_mul_f32_e32 v76, v80, v87
	v_add_f32_dpp v68, v68, v68 row_shr:4 row_mask:0xf bank_mask:0xf bound_ctrl:1
	v_add_f32_e32 v87, -1.0, v87
	v_fma_f32 v87, v87, v174, 1.0
	v_add_f32_dpp v68, v68, v68 row_shr:8 row_mask:0xf bank_mask:0xf bound_ctrl:1
	v_mul_f32_e32 v87, v188, v87
	s_nop 0
	v_mov_b32_dpp v91, v68 row_newbcast:15 row_mask:0xf bank_mask:0xf bound_ctrl:1
	v_sub_f32_e32 v95, v68, v91
	v_mul_f32_e32 v95, 0x3fb8aa3b, v95
	v_exp_f32_e32 v95, v95
	s_nop 0
	v_mul_f32_e32 v97, v95, v76
	v_mul_f32_e32 v95, v95, v87
	v_mov_b32_e32 v183, v97
	v_mov_b32_e32 v184, v95
	s_and_saveexec_b64 s[58:59], s[40:41]
	s_cbranch_execz .LBB0_357
	v_mul_f32_e32 v91, 0xbfb8aa3b, v91
	v_exp_f32_e32 v91, v91
	v_lshl_add_u32 v94, v140, 2, v35
	ds_write_b32 v94, v91 offset:12848
.LBB0_357:
	s_or_b64 exec, exec, s[58:59]
	v_fmac_f32_e32 v187, v123, v69
	v_cvt_f32_f16_sdwa v69, v32 dst_sel:DWORD dst_unused:UNUSED_PAD src0_sel:WORD_1
	v_cvt_f32_f16_sdwa v38, v38 dst_sel:DWORD dst_unused:UNUSED_PAD src0_sel:WORD_1
	v_cvt_f32_f16_sdwa v42, v42 dst_sel:DWORD dst_unused:UNUSED_PAD src0_sel:WORD_1
	v_fmac_f32_e32 v187, v124, v73
	v_cvt_f32_f16_sdwa v50, v50 dst_sel:DWORD dst_unused:UNUSED_PAD src0_sel:WORD_1
	v_sub_f32_e32 v38, v38, v69
	v_fma_mix_f32 v73, v38, v77, v32 op_sel:[0,0,1] op_sel_hi:[0,0,1]
	v_sub_f32_e32 v32, v42, v69
	v_cvt_f32_f16_sdwa v38, v46 dst_sel:DWORD dst_unused:UNUSED_PAD src0_sel:WORD_1
	v_fmac_f32_e32 v73, v32, v81
	v_cvt_pk_bf16_f32 v152, v254, v73
	v_add_f32_dpp v32, v38, v38 row_shr:1 row_mask:0xf bank_mask:0xf bound_ctrl:1
	s_waitcnt vmcnt(0)
	v_mul_f32_e32 v42, v187, v251
	v_add_f32_dpp v32, v32, v32 row_shr:2 row_mask:0xf bank_mask:0xf bound_ctrl:1
	v_mul_f32_e32 v46, v118, v42
	v_mul_f32_e32 v42, v46, v50
	v_add_f32_dpp v32, v32, v32 row_shr:4 row_mask:0xf bank_mask:0xf bound_ctrl:1
	v_add_f32_e32 v50, -1.0, v50
	s_waitcnt vmcnt(0)
	v_fma_f32 v50, v50, v175, 1.0
	v_add_f32_dpp v32, v32, v32 row_shr:8 row_mask:0xf bank_mask:0xf bound_ctrl:1
	v_mul_f32_e32 v50, v187, v50
	s_nop 0
	v_mov_b32_dpp v69, v32 row_newbcast:15 row_mask:0xf bank_mask:0xf bound_ctrl:1
	v_sub_f32_e32 v77, v32, v69
	v_mul_f32_e32 v77, 0x3fb8aa3b, v77
	v_exp_f32_e32 v77, v77
	s_nop 0
	v_mul_f32_e32 v81, v77, v42
	v_mul_f32_e32 v77, v77, v50
	v_cvt_pk_bf16_f32 v2, v183, v81
	v_cvt_pk_bf16_f32 v4, v184, v77
	s_and_saveexec_b64 s[58:59], s[40:41]
	s_cbranch_execz .LBB0_359
	v_mul_f32_e32 v69, 0xbfb8aa3b, v69
	v_exp_f32_e32 v69, v69
	v_lshl_add_u32 v73, v140, 2, v35
	ds_write_b32 v73, v69 offset:12852
.LBB0_359:
	s_or_b64 exec, exec, s[58:59]
	v_fmac_f32_e32 v186, v121, v70
	v_cvt_f32_f16_e32 v69, v33
	v_cvt_f32_f16_e32 v70, v39
	v_cvt_f32_f16_e32 v73, v43
	v_cvt_f32_f16_e32 v77, v51
	v_fmac_f32_e32 v186, v122, v74
	v_sub_f32_e32 v70, v70, v69
	v_sub_f32_e32 v69, v73, v69
	v_fma_mix_f32 v81, v70, v78, v33 op_sel_hi:[0,0,1]
	v_fmac_f32_e32 v81, v69, v82
	v_cvt_f32_f16_e32 v70, v47
	v_mov_b32_e32 v254, v81
	s_waitcnt vmcnt(0)
	v_mul_f32_e32 v73, v186, v252
	v_add_f32_dpp v69, v70, v70 row_shr:1 row_mask:0xf bank_mask:0xf bound_ctrl:1
	v_mul_f32_e32 v74, v118, v73
	v_mul_f32_e32 v73, v74, v77
	v_add_f32_dpp v69, v69, v69 row_shr:2 row_mask:0xf bank_mask:0xf bound_ctrl:1
	v_add_f32_e32 v77, -1.0, v77
	s_waitcnt vmcnt(0)
	v_fma_f32 v77, v77, v176, 1.0
	v_add_f32_dpp v69, v69, v69 row_shr:4 row_mask:0xf bank_mask:0xf bound_ctrl:1
	v_mul_f32_e32 v77, v186, v77
	s_nop 0
	v_add_f32_dpp v69, v69, v69 row_shr:8 row_mask:0xf bank_mask:0xf bound_ctrl:1
	s_nop 1
	v_mov_b32_dpp v78, v69 row_newbcast:15 row_mask:0xf bank_mask:0xf bound_ctrl:1
	v_sub_f32_e32 v82, v69, v78
	v_mul_f32_e32 v82, 0x3fb8aa3b, v82
	v_exp_f32_e32 v82, v82
	s_nop 0
	v_mul_f32_e32 v91, v82, v73
	v_mul_f32_e32 v82, v82, v77
	v_mov_b32_e32 v183, v91
	v_mov_b32_e32 v184, v82
	s_and_saveexec_b64 s[58:59], s[40:41]
	s_cbranch_execz .LBB0_361
	v_mul_f32_e32 v78, 0xbfb8aa3b, v78
	v_exp_f32_e32 v78, v78
	v_lshl_add_u32 v81, v140, 2, v35
	ds_write_b32 v81, v78 offset:12856
.LBB0_361:
	s_or_b64 exec, exec, s[58:59]
	v_fmac_f32_e32 v185, v119, v71
	v_cvt_f32_f16_sdwa v71, v33 dst_sel:DWORD dst_unused:UNUSED_PAD src0_sel:WORD_1
	v_cvt_f32_f16_sdwa v39, v39 dst_sel:DWORD dst_unused:UNUSED_PAD src0_sel:WORD_1
	v_fmac_f32_e32 v185, v120, v75
	v_cvt_f32_f16_sdwa v43, v43 dst_sel:DWORD dst_unused:UNUSED_PAD src0_sel:WORD_1
	v_sub_f32_e32 v39, v39, v71
	v_fma_mix_f32 v75, v39, v79, v33 op_sel:[0,0,1] op_sel_hi:[0,0,1]
	v_cvt_f32_f16_sdwa v39, v47 dst_sel:DWORD dst_unused:UNUSED_PAD src0_sel:WORD_1
	v_sub_f32_e32 v33, v43, v71
	v_fmac_f32_e32 v75, v33, v83
	v_cvt_f32_f16_sdwa v71, v51 dst_sel:DWORD dst_unused:UNUSED_PAD src0_sel:WORD_1
	v_add_f32_dpp v33, v39, v39 row_shr:1 row_mask:0xf bank_mask:0xf bound_ctrl:1
	v_cvt_pk_bf16_f32 v153, v254, v75
	s_waitcnt vmcnt(0)
	v_mul_f32_e32 v47, v185, v253
	v_add_f32_dpp v33, v33, v33 row_shr:2 row_mask:0xf bank_mask:0xf bound_ctrl:1
	v_mul_f32_e32 v51, v118, v47
	v_mul_f32_e32 v47, v51, v71
	v_add_f32_dpp v33, v33, v33 row_shr:4 row_mask:0xf bank_mask:0xf bound_ctrl:1
	v_add_f32_e32 v71, -1.0, v71
	v_fma_f32 v71, v71, v177, 1.0
	v_add_f32_dpp v33, v33, v33 row_shr:8 row_mask:0xf bank_mask:0xf bound_ctrl:1
	v_mul_f32_e32 v71, v185, v71
	s_nop 0
	v_mov_b32_dpp v43, v33 row_newbcast:15 row_mask:0xf bank_mask:0xf bound_ctrl:1
	v_sub_f32_e32 v78, v33, v43
	v_mul_f32_e32 v78, 0x3fb8aa3b, v78
	v_exp_f32_e32 v78, v78
	s_nop 0
	v_mul_f32_e32 v79, v78, v47
	v_mul_f32_e32 v78, v78, v71
	v_cvt_pk_bf16_f32 v3, v183, v79
	v_cvt_pk_bf16_f32 v5, v184, v78
	ds_write_b64 v255, v[2:3] offset:4632
	ds_write_b64 v255, v[4:5] offset:6808
	ds_write_b64 v255, v[152:153] offset:9752
	s_and_saveexec_b64 s[58:59], s[40:41]
	s_cbranch_execz .LBB0_363
	v_mul_f32_e32 v43, 0xbfb8aa3b, v43
	v_exp_f32_e32 v43, v43
	v_lshl_add_u32 v75, v140, 2, v35
	ds_write_b32 v75, v43 offset:12860

.LBB0_364:
	s_andn2_saveexec_b64 s[58:59], s[82:83]
	s_cbranch_execz .LBB0_304
	s_cmp_eq_u32 s97, 0
	s_cbranch_scc1 .LBB0_304
	s_mov_b32 s33, 4
	s_cmp_lt_i32 s33, 1
	s_cbranch_scc1 .LBB0_304
	v_lshrrev_b32_e32 v246, 2, v217
	v_mul_u32_u24_e32 v246, 0x88, v246
	v_and_b32_e32 v247, 3, v217
	v_lshl_add_u32 v246, v247, 3, v246
	v_lshrrev_b32_e32 v247, 1, v1
	v_and_b32_e32 v247, 0x60, v247
	v_add_u32_e32 v247, v247, v246
	v_add_u32_e32 v247, 0x2600, v247
	v_add_u32_e32 v246, 0x1200, v246
	s_lshl_b32 s60, s76, 14
	s_and_b32 s60, s60, 0x10000
	s_add_i32 s60, s60, 0
	v_mov_b32_e32 v18, v183
	v_mov_b32_e32 v19, v184
.LBB0_368:
	v_add_u32_e32 v44, s60, v176
	v_add_u32_e32 v248, s60, v246
	v_add_u32_e32 v28, s60, v247
	ds_read_b64_tr_b16 v[28:29], v28
	ds_read2_b64 v[30:33], v44 offset1:4
	ds_read2_b64 v[36:39], v44 offset0:8 offset1:12
	v_cvt_pk_bf16_f32 v20, v2, v3
	v_cvt_pk_bf16_f32 v21, v4, v5
	v_cvt_pk_bf16_f32 v22, v6, v7
	v_cvt_pk_bf16_f32 v23, v8, v9
	v_cvt_pk_bf16_f32 v24, v10, v11
	v_cvt_pk_bf16_f32 v25, v12, v13
	s_waitcnt lgkmcnt(1)
	v_mfma_f32_16x16x32_bf16 v[30:33], v[30:33], v[20:23], 0
	v_cvt_pk_bf16_f32 v26, v14, v15
	v_cvt_pk_bf16_f32 v27, v16, v17
	v_mov_b32_e32 v35, v34
	s_add_i32 s33, s33, -1
	s_waitcnt lgkmcnt(0)
	v_mfma_f32_16x16x32_bf16 v[36:39], v[36:39], v[24:27], v[30:33]
	s_nop 2
	v_add_u32_e32 v30, s60, v177
	ds_read2_b64 v[40:43], v30 offset1:96
	v_mov_b32_e32 v30, v34
	v_mov_b32_e32 v31, v34
	s_waitcnt lgkmcnt(0)
	v_mov_b32_e32 v32, v40
	v_mov_b32_e32 v33, v41
	s_nop 1
	v_mfma_f32_16x16x32_bf16 v[36:39], v[32:35], v[28:31], v[36:39]
	v_mov_b32_e32 v32, v42
	v_mov_b32_e32 v33, v43
	s_nop 5
	v_cvt_pk_bf16_f32 v36, v36, v37
	v_cvt_pk_bf16_f32 v37, v38, v39
	v_mov_b32_e32 v38, v34
	v_mov_b32_e32 v39, v34
	s_nop 1
	v_mfma_f32_16x16x32_bf16 v[30:33], v[32:35], v[36:39], 0
	s_nop 7
	v_cvt_pk_bf16_f32 v30, v30, v31
	v_cvt_pk_bf16_f32 v31, v32, v33
	v_mov_b32_e32 v32, v28
	v_mov_b32_e32 v33, v29
	v_add_u32_e32 v28, 0x800, v44
	v_add_u32_e32 v29, s60, v140
	ds_read2_b64 v[36:39], v28 offset0:32 offset1:36
	ds_read2_b64 v[40:43], v28 offset0:40 offset1:44
	ds_read_b128 v[48:51], v29 offset:12800
	v_add_u32_e32 v28, s60, v174
	ds_read_b128 v[44:47], v28 offset:9984
	s_waitcnt lgkmcnt(3)
	v_mfma_f32_16x16x32_bf16 v[20:23], v[36:39], v[20:23], 0
	s_addk_i32 s60, 0x4000
	s_waitcnt lgkmcnt(1)
	v_pk_mul_f32 v[4:5], v[4:5], v[50:51]
	v_pk_mul_f32 v[2:3], v[2:3], v[48:49]
	ds_read_b64_tr_b16 v[48:49], v248 offset:0
	ds_read_b64_tr_b16 v[50:51], v248 offset:2176
	v_mfma_f32_16x16x32_bf16 v[20:23], v[40:43], v[24:27], v[20:23]
	v_add_u32_e32 v24, 3, v18
	v_cndmask_b32_e64 v24, v24, v19, s[56:57]
	v_ashrrev_i32_e32 v25, 31, v24
	s_waitcnt lgkmcnt(0)
	v_mfma_f32_16x16x32_bf16 v[2:5], v[48:51], v[30:33], v[2:5]
	ds_read_b128 v[48:51], v29 offset:12864
	v_lshl_add_u64 v[24:25], s[22:23], 0, v[24:25]
	v_mad_u64_u32 v[26:27], s[64:65], v24, s89, v[152:153]
	v_mfma_f32_16x16x32_bf16 v[20:23], v[44:47], v[30:33], v[20:23]
	s_waitcnt lgkmcnt(0)
	v_pk_mul_f32 v[8:9], v[8:9], v[50:51]
	v_pk_mul_f32 v[6:7], v[6:7], v[48:49]
	ds_read_b64_tr_b16 v[48:49], v248 offset:32
	ds_read_b64_tr_b16 v[50:51], v248 offset:2208
	v_mad_i32_i24 v27, v25, s89, v27
	s_waitcnt lgkmcnt(0)
	v_mfma_f32_16x16x32_bf16 v[6:9], v[48:51], v[30:33], v[6:9]
	ds_read_b128 v[48:51], v29 offset:12928
	v_cvt_f16_f32_e32 v20, v20
	v_add_u32_e32 v24, 2, v18
	v_cvt_f16_f32_e32 v22, v22
	s_cmp_eq_u32 s33, 0
	s_waitcnt lgkmcnt(0)
	v_pk_mul_f32 v[12:13], v[12:13], v[50:51]
	v_pk_mul_f32 v[10:11], v[10:11], v[48:49]
	ds_read_b64_tr_b16 v[48:49], v248 offset:64
	ds_read_b64_tr_b16 v[50:51], v248 offset:2240
	global_store_short v[26:27], v20, off
	s_waitcnt lgkmcnt(0)
	v_mfma_f32_16x16x32_bf16 v[10:13], v[48:51], v[30:33], v[10:13]
	ds_read_b128 v[48:51], v29 offset:12992
	v_add_u32_e32 v20, 1, v19
	v_cndmask_b32_e64 v20, v24, v20, s[56:57]
	v_cvt_f16_f32_e32 v26, v21
	v_ashrrev_i32_e32 v21, 31, v20
	s_waitcnt lgkmcnt(0)
	v_pk_mul_f32 v[16:17], v[16:17], v[50:51]
	v_pk_mul_f32 v[14:15], v[14:15], v[48:49]
	ds_read_b64_tr_b16 v[48:49], v248 offset:96
	ds_read_b64_tr_b16 v[50:51], v248 offset:2272
	v_lshl_add_u64 v[20:21], s[22:23], 0, v[20:21]
	v_mad_u64_u32 v[24:25], s[64:65], v20, s89, v[152:153]
	v_mad_i32_i24 v25, v21, s89, v25
	v_add_u32_e32 v20, 2, v19
	v_add_u32_e32 v21, 1, v18
	v_cndmask_b32_e64 v20, v21, v20, s[56:57]
	v_ashrrev_i32_e32 v21, 31, v20
	v_lshl_add_u64 v[20:21], s[22:23], 0, v[20:21]
	global_store_short v[24:25], v26, off
	v_mad_u64_u32 v[24:25], s[64:65], v20, s89, v[152:153]
	v_add_u32_e32 v20, 3, v19
	v_mad_i32_i24 v25, v21, s89, v25
	v_cndmask_b32_e64 v20, v18, v20, s[56:57]
	s_waitcnt lgkmcnt(0)
	v_mfma_f32_16x16x32_bf16 v[14:17], v[48:51], v[30:33], v[14:17]
	global_store_short v[24:25], v22, off
	v_cvt_f16_f32_e32 v24, v23
	v_ashrrev_i32_e32 v21, 31, v20
	v_lshl_add_u64 v[20:21], s[22:23], 0, v[20:21]
	v_mad_u64_u32 v[22:23], s[64:65], v20, s89, v[152:153]
	v_mad_i32_i24 v23, v21, s89, v23
	v_add_u32_e32 v19, 16, v19
	v_add_u32_e32 v18, -16, v18
	global_store_short v[22:23], v24, off
	s_cbranch_scc0 .LBB0_368
	s_branch .LBB0_304

.LBB0_795:
	s_mov_b32 s98, 0
	v_mov_b32_e32 v2, v1
	s_load_dword s2, s[72:73], 0x10
	v_ashrrev_i32_e32 v3, 1, v2
	v_and_b32_e32 v4, 15, v2
	v_and_or_b32 v35, v3, s87, v4
	v_lshrrev_b32_e32 v3, 1, v2
	s_waitcnt lgkmcnt(0)
	s_lshr_b32 s2, s2, 16
	s_cmp_lg_u32 s2, 0
	s_cselect_b64 s[2:3], -1, 0
	s_cmp_lg_u64 s[2:3], 0
	s_addc_u32 s2, s74, 0
	s_lshr_b32 s33, s2, 3
	v_and_b32_e32 v3, 24, v3
	s_movk_i32 s2, 0xc0
	s_mov_b32 s24, 0
	v_and_or_b32 v226, v2, s2, v3
	s_branch .LBB0_797

.LBB0_802:
	s_cmp_eq_u32 s98, 1
	s_cbranch_scc1 .Lnxk0_pre
	v_mov_b32_e32 v15, v1
	s_load_dwordx2 s[38:39], s[0:1], 0xf8
	s_ashr_i32 s3, s2, 31
	v_ashrrev_i32_e32 v3, 3, v15
	v_and_b32_e32 v4, 7, v15
	v_lshlrev_b32_e32 v2, 1, v3
	s_lshl_b64 s[28:29], s[2:3], 19
	v_lshlrev_b32_e32 v227, 3, v4
	v_and_b32_e32 v14, 24, v2
	v_lshrrev_b32_e32 v2, 2, v3
	v_lshlrev_b32_e32 v228, 10, v3
	s_add_u32 s28, s16, s28
	v_and_b32_e32 v16, 4, v2
	v_and_b32_e32 v17, 35, v3
	v_or_b32_e32 v2, v228, v227
	v_bitop3_b32 v3, v3, v15, 7 bitop3:0x78
	s_addc_u32 s29, s17, s29
	v_or3_b32 v5, v17, v14, v16
	v_lshl_add_u32 v9, v4, 8, v3
	v_mov_b32_e32 v3, v34
	v_add_u32_e32 v6, 0x10000, v2
	v_mov_b32_e32 v7, v34
	v_lshl_or_b32 v8, v5, 10, v227
	s_mov_b32 s3, 16
	v_lshl_add_u64 v[4:5], v[2:3], 1, s[28:29]
	v_lshl_add_u64 v[6:7], v[6:7], 1, s[28:29]
	global_load_dwordx4 v[100:103], v[4:5], off
	global_load_dwordx4 v[108:111], v[6:7], off
	v_add_u32_e32 v6, 0x20000, v2
	v_mov_b32_e32 v7, v34
	v_lshl_add_u64 v[6:7], v[6:7], 1, s[28:29]
	s_ashr_i32 s23, s22, 31
	global_load_dwordx4 v[116:119], v[6:7], off
	v_add_u32_e32 v6, 0x30000, v2
	v_mov_b32_e32 v7, v34
	s_lshl_b64 s[30:31], s[22:23], 19
	v_lshl_add_u64 v[6:7], v[6:7], 1, s[28:29]
	s_waitcnt lgkmcnt(0)
	s_add_u32 s30, s38, s30
	global_load_dwordx4 v[124:127], v[6:7], off
	v_lshlrev_b32_e32 v6, 1, v8
	s_addc_u32 s31, s39, s31
	v_or_b32_e32 v8, 0x20000, v6
	v_or_b32_e32 v10, 0x40000, v6
	v_or_b32_e32 v12, 0x60000, v6
	global_load_dwordx4 v[132:135], v6, s[30:31]
	global_load_dwordx4 v[144:147], v8, s[30:31]
	global_load_dwordx4 v[148:151], v10, s[30:31]
	global_load_dwordx4 v[160:163], v12, s[30:31]
	v_lshl_add_u32 v229, v9, 4, 0
	v_add_u32_e32 v230, 0x10000, v229
	s_cmp_lt_i32 s3, 2
	s_waitcnt vmcnt(7)
	ds_write_b128 v229, v[100:103]
	s_waitcnt vmcnt(6)
	ds_write_b128 v229, v[108:111] offset:1024
	s_waitcnt vmcnt(5)
	ds_write_b128 v229, v[116:119] offset:2048
	s_waitcnt vmcnt(4)
	ds_write_b128 v229, v[124:127] offset:3072
	s_waitcnt vmcnt(3)
	ds_write_b128 v230, v[132:135]
	s_waitcnt vmcnt(2)
	ds_write_b128 v230, v[144:147] offset:1024
	s_waitcnt vmcnt(1)
	ds_write_b128 v230, v[148:151] offset:2048
	s_waitcnt vmcnt(0)
	ds_write_b128 v230, v[160:163] offset:3072
	s_cbranch_scc1 .LBB0_804
	v_add_u32_e32 v20, 0x20040, v2
	v_mov_b32_e32 v21, v34
	v_mov_b32_e32 v7, v34
	v_mov_b32_e32 v9, v34
	v_mov_b32_e32 v11, v34
	v_mov_b32_e32 v13, v34
	v_add_u32_e32 v18, 0x10040, v2
	v_mov_b32_e32 v19, v34
	v_lshl_add_u64 v[20:21], v[20:21], 1, s[28:29]
	v_add_u32_e32 v2, 0x30040, v2
	v_mov_b32_e32 v3, v34
	v_lshl_add_u64 v[6:7], s[30:31], 0, v[6:7]
	v_lshl_add_u64 v[8:9], s[30:31], 0, v[8:9]
	v_lshl_add_u64 v[10:11], s[30:31], 0, v[10:11]
	v_lshl_add_u64 v[12:13], s[30:31], 0, v[12:13]
	v_lshl_add_u64 v[18:19], v[18:19], 1, s[28:29]
	v_lshl_add_u64 v[2:3], v[2:3], 1, s[28:29]
	global_load_dwordx4 v[100:103], v[4:5], off offset:128
	global_load_dwordx4 v[108:111], v[18:19], off
	global_load_dwordx4 v[116:119], v[20:21], off
	global_load_dwordx4 v[124:127], v[2:3], off
	global_load_dwordx4 v[132:135], v[6:7], off offset:128
	global_load_dwordx4 v[144:147], v[8:9], off offset:128
	global_load_dwordx4 v[148:151], v[10:11], off offset:128
	global_load_dwordx4 v[160:163], v[12:13], off offset:128

.Lnxk0_pre:
	s_mov_b32 s98, 0
	v_mov_b32_e32 v15, v1
	s_load_dwordx2 s[38:39], s[0:1], 0xf8
	s_ashr_i32 s3, s2, 31
	v_ashrrev_i32_e32 v3, 3, v15
	v_and_b32_e32 v4, 7, v15
	v_lshlrev_b32_e32 v2, 1, v3
	s_lshl_b64 s[28:29], s[2:3], 19
	v_lshlrev_b32_e32 v227, 3, v4
	v_and_b32_e32 v14, 24, v2
	v_lshrrev_b32_e32 v2, 2, v3
	v_lshlrev_b32_e32 v228, 10, v3
	s_add_u32 s28, s16, s28
	v_and_b32_e32 v16, 4, v2
	v_and_b32_e32 v17, 35, v3
	v_or_b32_e32 v2, v228, v227
	v_bitop3_b32 v3, v3, v15, 7 bitop3:0x78
	s_addc_u32 s29, s17, s29
	v_or3_b32 v5, v17, v14, v16
	v_lshl_add_u32 v9, v4, 8, v3
	v_mov_b32_e32 v3, v34
	v_add_u32_e32 v6, 0x10000, v2
	v_mov_b32_e32 v7, v34
	v_lshl_or_b32 v8, v5, 10, v227
	s_mov_b32 s3, 16
	v_lshl_add_u64 v[4:5], v[2:3], 1, s[28:29]
	v_lshl_add_u64 v[6:7], v[6:7], 1, s[28:29]
	v_add_u32_e32 v6, 0x20000, v2
	v_mov_b32_e32 v7, v34
	v_lshl_add_u64 v[6:7], v[6:7], 1, s[28:29]
	s_ashr_i32 s23, s22, 31
	v_add_u32_e32 v6, 0x30000, v2
	v_mov_b32_e32 v7, v34
	s_lshl_b64 s[30:31], s[22:23], 19
	v_lshl_add_u64 v[6:7], v[6:7], 1, s[28:29]
	s_waitcnt lgkmcnt(0)
	s_add_u32 s30, s38, s30
	v_lshlrev_b32_e32 v6, 1, v8
	s_addc_u32 s31, s39, s31
	v_or_b32_e32 v8, 0x20000, v6
	v_or_b32_e32 v10, 0x40000, v6
	v_or_b32_e32 v12, 0x60000, v6
	v_lshl_add_u32 v229, v9, 4, 0
	v_add_u32_e32 v230, 0x10000, v229
	s_cmp_lt_i32 s3, 2
	s_waitcnt vmcnt(23)
	ds_write_b128 v229, v[164:167]
	s_waitcnt vmcnt(22)
	ds_write_b128 v229, v[168:171] offset:1024
	s_waitcnt vmcnt(21)
	ds_write_b128 v229, v[172:175] offset:2048
	s_waitcnt vmcnt(20)
	ds_write_b128 v229, v[192:195] offset:3072
	s_waitcnt vmcnt(19)
	ds_write_b128 v230, v[176:179]
	s_waitcnt vmcnt(18)
	ds_write_b128 v230, v[180:183] offset:1024
	s_waitcnt vmcnt(17)
	ds_write_b128 v230, v[184:187] offset:2048
	s_waitcnt vmcnt(16)
	ds_write_b128 v230, v[188:191] offset:3072
	s_cbranch_scc1 .LBB0_804
	v_add_u32_e32 v20, 0x20040, v2
	v_mov_b32_e32 v21, v34
	v_mov_b32_e32 v7, v34
	v_mov_b32_e32 v9, v34
	v_mov_b32_e32 v11, v34
	v_mov_b32_e32 v13, v34
	v_add_u32_e32 v18, 0x10040, v2
	v_mov_b32_e32 v19, v34
	v_lshl_add_u64 v[20:21], v[20:21], 1, s[28:29]
	v_add_u32_e32 v2, 0x30040, v2
	v_mov_b32_e32 v3, v34
	v_lshl_add_u64 v[6:7], s[30:31], 0, v[6:7]
	v_lshl_add_u64 v[8:9], s[30:31], 0, v[8:9]
	v_lshl_add_u64 v[10:11], s[30:31], 0, v[10:11]
	v_lshl_add_u64 v[12:13], s[30:31], 0, v[12:13]
	v_lshl_add_u64 v[18:19], v[18:19], 1, s[28:29]
	v_lshl_add_u64 v[2:3], v[2:3], 1, s[28:29]
	global_load_dwordx4 v[100:103], v[4:5], off offset:128
	global_load_dwordx4 v[108:111], v[18:19], off
	global_load_dwordx4 v[116:119], v[20:21], off
	global_load_dwordx4 v[124:127], v[2:3], off
	global_load_dwordx4 v[132:135], v[6:7], off offset:128
	global_load_dwordx4 v[144:147], v[8:9], off offset:128
	global_load_dwordx4 v[148:151], v[10:11], off offset:128
	global_load_dwordx4 v[160:163], v[12:13], off offset:128
	s_branch .LBB0_804

.LBB0_812:
	s_waitcnt vmcnt(1)
	s_add_i32 s3, s24, 1
	s_mul_i32 s23, s3, s33
	s_mul_hi_u32 s3, s3, s33
	s_add_u32 s30, s23, s37
	s_addc_u32 s31, s3, 0
	s_lshr_b64 s[28:29], s[30:31], 2
	s_and_b32 s3, s28, -8
	s_or_b32 s23, s3, s35
	s_mov_b32 s98, 0
	s_cmp_gt_i32 s23, 63
	s_cbranch_scc1 .Lnxk0_skip
	s_cmp_eq_u32 s22, 15
	s_cbranch_scc1 .Lnxk0_skip
	s_load_dwordx2 s[100:101], s[0:1], 0xf8
	s_lshr_b32 s3, s23, 1
	s_lshl_b32 s3, s3, 2
	s_and_b32 s28, s30, 3
	s_or_b32 s3, s3, s28
	s_and_b32 s28, s23, 1
	s_lshl_b32 s28, s28, 3
	s_bfe_u32 s29, s30, 0x30002
	s_or_b32 s28, s28, s29
	s_lshl_b32 s3, s3, 19
	s_lshl_b32 s28, s28, 19
	s_add_u32 s98, s16, s3
	s_addc_u32 s99, s17, 0
	s_waitcnt lgkmcnt(0)
	s_add_u32 s100, s100, s28
	s_addc_u32 s101, s101, 0
	s_sub_u32 s98, s98, 1920
	s_subb_u32 s99, s99, 0
	s_sub_u32 s100, s100, 1920
	s_subb_u32 s101, s101, 0
	v_add_u32_e32 v246, v227, v228
	v_add_u32_e32 v247, v227, v231
	v_lshlrev_b32_e32 v246, 1, v246
	v_lshlrev_b32_e32 v247, 1, v247
	v_add_u32_e32 v248, 0x20000, v246
	v_add_u32_e32 v249, 0x40000, v246
	v_add_u32_e32 v250, 0x60000, v246
	v_add_u32_e32 v251, 0x20000, v247
	v_add_u32_e32 v252, 0x40000, v247
	v_add_u32_e32 v253, 0x60000, v247
	global_load_dwordx4 v[164:167], v246, s[98:99]
	global_load_dwordx4 v[168:171], v248, s[98:99]
	global_load_dwordx4 v[172:175], v249, s[98:99]
	global_load_dwordx4 v[192:195], v250, s[98:99]
	global_load_dwordx4 v[176:179], v247, s[100:101]
	global_load_dwordx4 v[180:183], v251, s[100:101]
	global_load_dwordx4 v[184:187], v252, s[100:101]
	global_load_dwordx4 v[188:191], v253, s[100:101]
	s_mov_b32 s98, 1
.Lnxk0_skip:
	v_lshl_add_u32 v108, s2, 8, v35
	v_lshl_or_b32 v100, s22, 8, v226
	v_mov_b64_e32 v[102:103], s[18:19]
	v_mad_i64_i32 v[102:103], s[28:29], v108, s89, v[102:103]
	v_cmp_gt_i32_e32 vcc, s88, v100
	s_and_saveexec_b64 s[28:29], vcc
	s_cbranch_execz .LBB0_814
	v_ashrrev_i32_e32 v101, 31, v100
	v_lshl_add_u64 v[110:111], v[100:101], 1, v[102:103]
	v_cvt_pk_f16_f32 v116, v156, v157
	v_cvt_pk_f16_f32 v117, v158, v159
	v_cvt_pk_f16_f32 v118, v152, v153
	v_cvt_pk_f16_f32 v119, v154, v155
	global_store_dwordx4 v[110:111], v[116:119], off
